# keep_v10 + s_setprio 0 placed before the last MFMA of each compute segment, so the wave goes from its last MFMA straight to the closing barrier
# baseline (speedup 1.0000x reference)
.LBB0_182:
	s_add_u32 s6, s4, 0xfffc0080
	s_addc_u32 s7, s5, -1
	s_add_i32 s9, 0, 0x10000
	s_cmp_eq_u32 s53, 12
	s_cselect_b32 s27, s39, s7
	s_cselect_b32 s26, s49, s6
	v_add_u32_e32 v0, s9, v189
	s_cselect_b32 s7, s15, s52
	s_cselect_b32 s6, s50, s51
	s_add_i32 s83, 0, 0x14000
	ds_read_b128 v[130:133], v0
	ds_read_b128 v[134:137], v0 offset:1024
	ds_read_b128 v[162:165], v0 offset:2048
	ds_read_b128 v[166:169], v0 offset:3072
	v_add_u32_e32 v0, s83, v189
	ds_read_b128 v[170:173], v0
	ds_read_b128 v[174:177], v0 offset:1024
	ds_read_b128 v[178:181], v0 offset:2048
	ds_read_b128 v[182:185], v0 offset:3072
	v_lshl_add_u64 v[148:149], s[4:5], 0, v[158:159]
	s_add_i32 m0, s40, 0xc000
	ds_read_b128 v[196:199], v193
	ds_read_b128 v[200:203], v193 offset:1024
	ds_read_b128 v[204:207], v193 offset:2048
	ds_read_b128 v[208:211], v193 offset:3072
	ds_read_b128 v[212:215], v193 offset:4096
	ds_read_b128 v[216:219], v193 offset:5120
	ds_read_b128 v[220:223], v193 offset:6144
	ds_read_b128 v[224:227], v193 offset:7168
	global_load_lds_dwordx4 v[148:149], off
	s_add_i32 m0, s40, 0xe000
	v_lshl_add_u64 v[148:149], s[4:5], 0, v[160:161]
	global_load_lds_dwordx4 v[148:149], off
	s_waitcnt vmcnt(8)
	s_waitcnt lgkmcnt(0)
	s_setprio 1
	s_barrier
	v_mfma_f32_16x16x32_bf16 v[126:129], v[130:133], v[196:199], v[126:129]
	v_mfma_f32_16x16x32_bf16 v[122:125], v[162:165], v[196:199], v[122:125]
	v_mfma_f32_16x16x32_bf16 v[118:121], v[130:133], v[204:207], v[118:121]
	v_mfma_f32_16x16x32_bf16 v[114:117], v[162:165], v[204:207], v[114:117]
	v_mfma_f32_16x16x32_bf16 v[102:105], v[130:133], v[212:215], v[102:105]
	v_mfma_f32_16x16x32_bf16 v[98:101], v[162:165], v[212:215], v[98:101]
	v_mfma_f32_16x16x32_bf16 v[86:89], v[130:133], v[220:223], v[86:89]
	v_mfma_f32_16x16x32_bf16 v[82:85], v[162:165], v[220:223], v[82:85]
	v_mfma_f32_16x16x32_bf16 v[126:129], v[134:137], v[200:203], v[126:129]
	v_mfma_f32_16x16x32_bf16 v[122:125], v[166:169], v[200:203], v[122:125]
	v_mfma_f32_16x16x32_bf16 v[118:121], v[134:137], v[208:211], v[118:121]
	v_mfma_f32_16x16x32_bf16 v[114:117], v[166:169], v[208:211], v[114:117]
	v_mfma_f32_16x16x32_bf16 v[102:105], v[134:137], v[216:219], v[102:105]
	v_mfma_f32_16x16x32_bf16 v[98:101], v[166:169], v[216:219], v[98:101]
	v_mfma_f32_16x16x32_bf16 v[86:89], v[134:137], v[224:227], v[86:89]
	v_mfma_f32_16x16x32_bf16 v[82:85], v[166:169], v[224:227], v[82:85]
	v_mfma_f32_16x16x32_bf16 v[110:113], v[170:173], v[196:199], v[110:113]
	v_mfma_f32_16x16x32_bf16 v[106:109], v[178:181], v[196:199], v[106:109]
	v_mfma_f32_16x16x32_bf16 v[94:97], v[170:173], v[204:207], v[94:97]
	v_mfma_f32_16x16x32_bf16 v[90:93], v[178:181], v[204:207], v[90:93]
	v_mfma_f32_16x16x32_bf16 v[78:81], v[170:173], v[212:215], v[78:81]
	v_mfma_f32_16x16x32_bf16 v[74:77], v[178:181], v[212:215], v[74:77]
	v_mfma_f32_16x16x32_bf16 v[70:73], v[170:173], v[220:223], v[70:73]
	v_mfma_f32_16x16x32_bf16 v[66:69], v[178:181], v[220:223], v[66:69]
	v_mfma_f32_16x16x32_bf16 v[110:113], v[174:177], v[200:203], v[110:113]
	v_mfma_f32_16x16x32_bf16 v[106:109], v[182:185], v[200:203], v[106:109]
	v_mfma_f32_16x16x32_bf16 v[94:97], v[174:177], v[208:211], v[94:97]
	v_mfma_f32_16x16x32_bf16 v[90:93], v[182:185], v[208:211], v[90:93]
	v_mfma_f32_16x16x32_bf16 v[78:81], v[174:177], v[216:219], v[78:81]
	v_mfma_f32_16x16x32_bf16 v[74:77], v[182:185], v[216:219], v[74:77]
	v_mfma_f32_16x16x32_bf16 v[70:73], v[174:177], v[224:227], v[70:73]
	s_setprio 0
	v_mfma_f32_16x16x32_bf16 v[66:69], v[182:185], v[224:227], v[66:69]
	s_barrier
	s_add_i32 s9, s9, s29
	v_lshl_add_u64 v[148:149], s[6:7], 0, v[142:143]
	s_mov_b32 m0, s9
	ds_read_b128 v[196:199], v193 offset:16384
	ds_read_b128 v[200:203], v193 offset:17408
	ds_read_b128 v[204:207], v193 offset:18432
	ds_read_b128 v[208:211], v193 offset:19456
	ds_read_b128 v[212:215], v193 offset:20480
	ds_read_b128 v[216:219], v193 offset:21504
	ds_read_b128 v[220:223], v193 offset:22528
	ds_read_b128 v[224:227], v193 offset:23552
	global_load_lds_dwordx4 v[148:149], off
	s_add_i32 m0, s9, 0x2000
	s_add_u32 s78, s6, 0x40000
	v_lshl_add_u64 v[150:151], s[6:7], 0, v[138:139]
	s_addc_u32 s79, s7, 0
	s_add_i32 s9, s83, s29
	global_load_lds_dwordx4 v[150:151], off
	v_lshl_add_u64 v[186:187], s[78:79], 0, v[142:143]
	s_mov_b32 m0, s9
	v_lshl_add_u64 v[228:229], s[26:27], 0, v[140:141]
	global_load_lds_dwordx4 v[186:187], off
	s_add_i32 m0, s9, 0x2000
	v_lshl_add_u64 v[186:187], s[78:79], 0, v[138:139]
	global_load_lds_dwordx4 v[186:187], off
	s_mov_b32 m0, s40
	v_lshl_add_u64 v[186:187], s[26:27], 0, v[144:145]
	global_load_lds_dwordx4 v[186:187], off
	s_mov_b32 m0, s41
	s_nop 0
	global_load_lds_dwordx4 v[228:229], off
	s_waitcnt vmcnt(8)
	s_waitcnt lgkmcnt(0)
	s_setprio 1
	s_barrier
	v_mfma_f32_16x16x32_bf16 v[62:65], v[130:133], v[196:199], v[62:65]
	v_mfma_f32_16x16x32_bf16 v[58:61], v[162:165], v[196:199], v[58:61]
	v_mfma_f32_16x16x32_bf16 v[54:57], v[130:133], v[204:207], v[54:57]
	v_mfma_f32_16x16x32_bf16 v[50:53], v[162:165], v[204:207], v[50:53]
	v_mfma_f32_16x16x32_bf16 v[38:41], v[130:133], v[212:215], v[38:41]
	v_mfma_f32_16x16x32_bf16 v[34:37], v[162:165], v[212:215], v[34:37]
	v_mfma_f32_16x16x32_bf16 v[22:25], v[130:133], v[220:223], v[22:25]
	v_mfma_f32_16x16x32_bf16 v[18:21], v[162:165], v[220:223], v[18:21]
	v_mfma_f32_16x16x32_bf16 v[62:65], v[134:137], v[200:203], v[62:65]
	v_mfma_f32_16x16x32_bf16 v[58:61], v[166:169], v[200:203], v[58:61]
	v_mfma_f32_16x16x32_bf16 v[54:57], v[134:137], v[208:211], v[54:57]
	v_mfma_f32_16x16x32_bf16 v[50:53], v[166:169], v[208:211], v[50:53]
	v_mfma_f32_16x16x32_bf16 v[38:41], v[134:137], v[216:219], v[38:41]
	v_mfma_f32_16x16x32_bf16 v[34:37], v[166:169], v[216:219], v[34:37]
	v_mfma_f32_16x16x32_bf16 v[22:25], v[134:137], v[224:227], v[22:25]
	v_mfma_f32_16x16x32_bf16 v[18:21], v[166:169], v[224:227], v[18:21]
	v_mfma_f32_16x16x32_bf16 v[46:49], v[170:173], v[196:199], v[46:49]
	v_mfma_f32_16x16x32_bf16 v[42:45], v[178:181], v[196:199], v[42:45]
	v_mfma_f32_16x16x32_bf16 v[30:33], v[170:173], v[204:207], v[30:33]
	v_mfma_f32_16x16x32_bf16 v[26:29], v[178:181], v[204:207], v[26:29]
	v_mfma_f32_16x16x32_bf16 v[14:17], v[170:173], v[212:215], v[14:17]
	v_mfma_f32_16x16x32_bf16 v[10:13], v[178:181], v[212:215], v[10:13]
	v_mfma_f32_16x16x32_bf16 v[6:9], v[170:173], v[220:223], v[6:9]
	v_mfma_f32_16x16x32_bf16 v[2:5], v[178:181], v[220:223], v[2:5]
	v_mfma_f32_16x16x32_bf16 v[46:49], v[174:177], v[200:203], v[46:49]
	v_mfma_f32_16x16x32_bf16 v[42:45], v[182:185], v[200:203], v[42:45]
	v_mfma_f32_16x16x32_bf16 v[30:33], v[174:177], v[208:211], v[30:33]
	v_mfma_f32_16x16x32_bf16 v[26:29], v[182:185], v[208:211], v[26:29]
	v_mfma_f32_16x16x32_bf16 v[14:17], v[174:177], v[216:219], v[14:17]
	v_mfma_f32_16x16x32_bf16 v[10:13], v[182:185], v[216:219], v[10:13]
	v_mfma_f32_16x16x32_bf16 v[6:9], v[174:177], v[224:227], v[6:9]
	s_setprio 0
	v_mfma_f32_16x16x32_bf16 v[2:5], v[182:185], v[224:227], v[2:5]
	s_barrier
	s_add_i32 s9, 0, 0x18000
	v_add_u32_e32 v0, s9, v189
	s_add_i32 s78, 0, 0x1c000
	ds_read_b128 v[130:133], v0
	ds_read_b128 v[134:137], v0 offset:1024
	ds_read_b128 v[162:165], v0 offset:2048
	ds_read_b128 v[166:169], v0 offset:3072
	v_add_u32_e32 v0, s78, v189
	ds_read_b128 v[170:173], v0
	ds_read_b128 v[174:177], v0 offset:1024
	ds_read_b128 v[178:181], v0 offset:2048
	ds_read_b128 v[182:185], v0 offset:3072
	s_add_u32 s26, s26, 0x40000
	s_addc_u32 s27, s27, 0
	s_mov_b32 m0, s42
	v_lshl_add_u64 v[230:231], s[26:27], 0, v[144:145]
	ds_read_b128 v[196:199], v193 offset:32768
	ds_read_b128 v[200:203], v193 offset:33792
	ds_read_b128 v[204:207], v193 offset:34816
	ds_read_b128 v[208:211], v193 offset:35840
	ds_read_b128 v[212:215], v193 offset:36864
	ds_read_b128 v[216:219], v193 offset:37888
	ds_read_b128 v[220:223], v193 offset:38912
	ds_read_b128 v[224:227], v193 offset:39936
	global_load_lds_dwordx4 v[230:231], off
	s_mov_b32 m0, s43
	v_lshl_add_u64 v[230:231], s[26:27], 0, v[140:141]
	global_load_lds_dwordx4 v[230:231], off
	s_waitcnt vmcnt(8)
	s_waitcnt lgkmcnt(0)
	s_setprio 1
	s_barrier
	v_mfma_f32_16x16x32_bf16 v[126:129], v[130:133], v[196:199], v[126:129]
	v_mfma_f32_16x16x32_bf16 v[122:125], v[162:165], v[196:199], v[122:125]
	v_mfma_f32_16x16x32_bf16 v[118:121], v[130:133], v[204:207], v[118:121]
	v_mfma_f32_16x16x32_bf16 v[114:117], v[162:165], v[204:207], v[114:117]
	v_mfma_f32_16x16x32_bf16 v[102:105], v[130:133], v[212:215], v[102:105]
	v_mfma_f32_16x16x32_bf16 v[98:101], v[162:165], v[212:215], v[98:101]
	v_mfma_f32_16x16x32_bf16 v[86:89], v[130:133], v[220:223], v[86:89]
	v_mfma_f32_16x16x32_bf16 v[82:85], v[162:165], v[220:223], v[82:85]
	v_mfma_f32_16x16x32_bf16 v[126:129], v[134:137], v[200:203], v[126:129]
	v_mfma_f32_16x16x32_bf16 v[122:125], v[166:169], v[200:203], v[122:125]
	v_mfma_f32_16x16x32_bf16 v[118:121], v[134:137], v[208:211], v[118:121]
	v_mfma_f32_16x16x32_bf16 v[114:117], v[166:169], v[208:211], v[114:117]
	v_mfma_f32_16x16x32_bf16 v[102:105], v[134:137], v[216:219], v[102:105]
	v_mfma_f32_16x16x32_bf16 v[98:101], v[166:169], v[216:219], v[98:101]
	v_mfma_f32_16x16x32_bf16 v[86:89], v[134:137], v[224:227], v[86:89]
	v_mfma_f32_16x16x32_bf16 v[82:85], v[166:169], v[224:227], v[82:85]
	v_mfma_f32_16x16x32_bf16 v[110:113], v[170:173], v[196:199], v[110:113]
	v_mfma_f32_16x16x32_bf16 v[106:109], v[178:181], v[196:199], v[106:109]
	v_mfma_f32_16x16x32_bf16 v[94:97], v[170:173], v[204:207], v[94:97]
	v_mfma_f32_16x16x32_bf16 v[90:93], v[178:181], v[204:207], v[90:93]
	v_mfma_f32_16x16x32_bf16 v[78:81], v[170:173], v[212:215], v[78:81]
	v_mfma_f32_16x16x32_bf16 v[74:77], v[178:181], v[212:215], v[74:77]
	v_mfma_f32_16x16x32_bf16 v[70:73], v[170:173], v[220:223], v[70:73]
	v_mfma_f32_16x16x32_bf16 v[66:69], v[178:181], v[220:223], v[66:69]
	v_mfma_f32_16x16x32_bf16 v[110:113], v[174:177], v[200:203], v[110:113]
	v_mfma_f32_16x16x32_bf16 v[106:109], v[182:185], v[200:203], v[106:109]
	v_mfma_f32_16x16x32_bf16 v[94:97], v[174:177], v[208:211], v[94:97]
	v_mfma_f32_16x16x32_bf16 v[90:93], v[182:185], v[208:211], v[90:93]
	v_mfma_f32_16x16x32_bf16 v[78:81], v[174:177], v[216:219], v[78:81]
	v_mfma_f32_16x16x32_bf16 v[74:77], v[182:185], v[216:219], v[74:77]
	v_mfma_f32_16x16x32_bf16 v[70:73], v[174:177], v[224:227], v[70:73]
	s_setprio 0
	v_mfma_f32_16x16x32_bf16 v[66:69], v[182:185], v[224:227], v[66:69]
	s_barrier
	s_add_i32 s9, s9, s29
	v_lshl_add_u64 v[148:149], v[148:149], 0, s[70:71]
	s_mov_b32 m0, s9
	ds_read_b128 v[196:199], v193 offset:49152
	ds_read_b128 v[200:203], v193 offset:50176
	ds_read_b128 v[204:207], v193 offset:51200
	ds_read_b128 v[208:211], v193 offset:52224
	ds_read_b128 v[212:215], v193 offset:53248
	ds_read_b128 v[216:219], v193 offset:54272
	ds_read_b128 v[220:223], v193 offset:55296
	ds_read_b128 v[224:227], v193 offset:56320
	global_load_lds_dwordx4 v[148:149], off
	s_add_i32 m0, s9, 0x2000
	s_add_u32 s6, s6, 0x40080
	v_lshl_add_u64 v[148:149], v[150:151], 0, s[70:71]
	s_addc_u32 s7, s7, 0
	s_add_i32 s9, s78, s29
	global_load_lds_dwordx4 v[148:149], off
	s_mov_b32 m0, s9
	v_lshl_add_u64 v[148:149], s[6:7], 0, v[142:143]
	global_load_lds_dwordx4 v[148:149], off
	s_add_i32 m0, s9, 0x2000
	v_lshl_add_u64 v[148:149], s[6:7], 0, v[138:139]
	global_load_lds_dwordx4 v[148:149], off
	s_mov_b32 m0, s44
	v_lshl_add_u64 v[148:149], v[186:187], 0, s[70:71]
	global_load_lds_dwordx4 v[148:149], off
	s_mov_b32 m0, s45
	v_lshl_add_u64 v[148:149], v[228:229], 0, s[70:71]
	global_load_lds_dwordx4 v[148:149], off
	s_waitcnt vmcnt(8)
	s_waitcnt lgkmcnt(0)
	s_setprio 1
	s_barrier
	v_mfma_f32_16x16x32_bf16 v[62:65], v[130:133], v[196:199], v[62:65]
	v_mfma_f32_16x16x32_bf16 v[58:61], v[162:165], v[196:199], v[58:61]
	v_mfma_f32_16x16x32_bf16 v[54:57], v[130:133], v[204:207], v[54:57]
	v_mfma_f32_16x16x32_bf16 v[50:53], v[162:165], v[204:207], v[50:53]
	v_mfma_f32_16x16x32_bf16 v[38:41], v[130:133], v[212:215], v[38:41]
	v_mfma_f32_16x16x32_bf16 v[34:37], v[162:165], v[212:215], v[34:37]
	v_mfma_f32_16x16x32_bf16 v[22:25], v[130:133], v[220:223], v[22:25]
	v_mfma_f32_16x16x32_bf16 v[18:21], v[162:165], v[220:223], v[18:21]
	v_mfma_f32_16x16x32_bf16 v[62:65], v[134:137], v[200:203], v[62:65]
	v_mfma_f32_16x16x32_bf16 v[58:61], v[166:169], v[200:203], v[58:61]
	v_mfma_f32_16x16x32_bf16 v[54:57], v[134:137], v[208:211], v[54:57]
	v_mfma_f32_16x16x32_bf16 v[50:53], v[166:169], v[208:211], v[50:53]
	v_mfma_f32_16x16x32_bf16 v[38:41], v[134:137], v[216:219], v[38:41]
	v_mfma_f32_16x16x32_bf16 v[34:37], v[166:169], v[216:219], v[34:37]
	v_mfma_f32_16x16x32_bf16 v[22:25], v[134:137], v[224:227], v[22:25]
	v_mfma_f32_16x16x32_bf16 v[18:21], v[166:169], v[224:227], v[18:21]
	v_mfma_f32_16x16x32_bf16 v[46:49], v[170:173], v[196:199], v[46:49]
	v_mfma_f32_16x16x32_bf16 v[42:45], v[178:181], v[196:199], v[42:45]
	v_mfma_f32_16x16x32_bf16 v[30:33], v[170:173], v[204:207], v[30:33]
	v_mfma_f32_16x16x32_bf16 v[26:29], v[178:181], v[204:207], v[26:29]
	v_mfma_f32_16x16x32_bf16 v[14:17], v[170:173], v[212:215], v[14:17]
	v_mfma_f32_16x16x32_bf16 v[10:13], v[178:181], v[212:215], v[10:13]
	v_mfma_f32_16x16x32_bf16 v[6:9], v[170:173], v[220:223], v[6:9]
	v_mfma_f32_16x16x32_bf16 v[2:5], v[178:181], v[220:223], v[2:5]
	v_mfma_f32_16x16x32_bf16 v[46:49], v[174:177], v[200:203], v[46:49]
	v_mfma_f32_16x16x32_bf16 v[42:45], v[182:185], v[200:203], v[42:45]
	v_mfma_f32_16x16x32_bf16 v[30:33], v[174:177], v[208:211], v[30:33]
	v_mfma_f32_16x16x32_bf16 v[26:29], v[182:185], v[208:211], v[26:29]
	v_mfma_f32_16x16x32_bf16 v[14:17], v[174:177], v[216:219], v[14:17]
	v_mfma_f32_16x16x32_bf16 v[10:13], v[182:185], v[216:219], v[10:13]
	v_mfma_f32_16x16x32_bf16 v[6:9], v[174:177], v[224:227], v[6:9]
	s_setprio 0
	v_mfma_f32_16x16x32_bf16 v[2:5], v[182:185], v[224:227], v[2:5]
	s_barrier
	s_add_i32 s53, s53, 2
	s_add_u32 s4, s4, 0x100
	s_addc_u32 s5, s5, 0
	s_add_u32 s51, s51, 0x100
	s_addc_u32 s52, s52, 0
	s_cmp_gt_u32 s53, 13
	s_cbranch_scc0 .LBB0_182
	s_and_b64 vcc, exec, s[36:37]
	s_cbranch_vccz .LBB0_185
	s_barrier

.LBB0_220:
	s_add_u32 s9, s36, 0xfffc0080
	s_addc_u32 s26, s37, -1
	s_add_i32 s60, 0, 0x10000
	s_cmp_eq_u32 s53, 12
	s_cselect_b32 s39, s19, s26
	s_cselect_b32 s38, s49, s9
	v_add_u32_e32 v148, s60, v141
	s_cselect_b32 s27, s17, s52
	s_cselect_b32 s26, s50, s51
	s_add_i32 s9, 0, 0x14000
	ds_read_b128 v[144:147], v148
	ds_read_b128 v[156:159], v148 offset:1024
	ds_read_b128 v[160:163], v148 offset:2048
	ds_read_b128 v[164:167], v148 offset:3072
	v_add_u32_e32 v148, s9, v141
	ds_read_b128 v[168:171], v148
	ds_read_b128 v[172:175], v148 offset:1024
	ds_read_b128 v[176:179], v148 offset:2048
	ds_read_b128 v[180:183], v148 offset:3072
	v_lshl_add_u64 v[148:149], s[36:37], 0, v[136:137]
	s_add_i32 m0, s40, 0xc000
	ds_read_b128 v[184:187], v143
	ds_read_b128 v[188:191], v143 offset:1024
	ds_read_b128 v[192:195], v143 offset:2048
	ds_read_b128 v[196:199], v143 offset:3072
	ds_read_b128 v[200:203], v143 offset:4096
	ds_read_b128 v[204:207], v143 offset:5120
	ds_read_b128 v[208:211], v143 offset:6144
	ds_read_b128 v[212:215], v143 offset:7168
	global_load_lds_dwordx4 v[148:149], off
	s_add_i32 m0, s40, 0xe000
	v_lshl_add_u64 v[148:149], s[36:37], 0, v[138:139]
	global_load_lds_dwordx4 v[148:149], off
	s_waitcnt vmcnt(8)
	s_waitcnt lgkmcnt(0)
	s_setprio 1
	s_barrier
	v_mfma_f32_16x16x32_bf16 v[126:129], v[144:147], v[184:187], v[126:129]
	v_mfma_f32_16x16x32_bf16 v[122:125], v[160:163], v[184:187], v[122:125]
	v_mfma_f32_16x16x32_bf16 v[118:121], v[144:147], v[192:195], v[118:121]
	v_mfma_f32_16x16x32_bf16 v[114:117], v[160:163], v[192:195], v[114:117]
	v_mfma_f32_16x16x32_bf16 v[102:105], v[144:147], v[200:203], v[102:105]
	v_mfma_f32_16x16x32_bf16 v[98:101], v[160:163], v[200:203], v[98:101]
	v_mfma_f32_16x16x32_bf16 v[86:89], v[144:147], v[208:211], v[86:89]
	v_mfma_f32_16x16x32_bf16 v[82:85], v[160:163], v[208:211], v[82:85]
	v_mfma_f32_16x16x32_bf16 v[126:129], v[156:159], v[188:191], v[126:129]
	v_mfma_f32_16x16x32_bf16 v[122:125], v[164:167], v[188:191], v[122:125]
	v_mfma_f32_16x16x32_bf16 v[118:121], v[156:159], v[196:199], v[118:121]
	v_mfma_f32_16x16x32_bf16 v[114:117], v[164:167], v[196:199], v[114:117]
	v_mfma_f32_16x16x32_bf16 v[102:105], v[156:159], v[204:207], v[102:105]
	v_mfma_f32_16x16x32_bf16 v[98:101], v[164:167], v[204:207], v[98:101]
	v_mfma_f32_16x16x32_bf16 v[86:89], v[156:159], v[212:215], v[86:89]
	v_mfma_f32_16x16x32_bf16 v[82:85], v[164:167], v[212:215], v[82:85]
	v_mfma_f32_16x16x32_bf16 v[110:113], v[168:171], v[184:187], v[110:113]
	v_mfma_f32_16x16x32_bf16 v[106:109], v[176:179], v[184:187], v[106:109]
	v_mfma_f32_16x16x32_bf16 v[94:97], v[168:171], v[192:195], v[94:97]
	v_mfma_f32_16x16x32_bf16 v[90:93], v[176:179], v[192:195], v[90:93]
	v_mfma_f32_16x16x32_bf16 v[78:81], v[168:171], v[200:203], v[78:81]
	v_mfma_f32_16x16x32_bf16 v[74:77], v[176:179], v[200:203], v[74:77]
	v_mfma_f32_16x16x32_bf16 v[70:73], v[168:171], v[208:211], v[70:73]
	v_mfma_f32_16x16x32_bf16 v[66:69], v[176:179], v[208:211], v[66:69]
	v_mfma_f32_16x16x32_bf16 v[110:113], v[172:175], v[188:191], v[110:113]
	v_mfma_f32_16x16x32_bf16 v[106:109], v[180:183], v[188:191], v[106:109]
	v_mfma_f32_16x16x32_bf16 v[94:97], v[172:175], v[196:199], v[94:97]
	v_mfma_f32_16x16x32_bf16 v[90:93], v[180:183], v[196:199], v[90:93]
	v_mfma_f32_16x16x32_bf16 v[78:81], v[172:175], v[204:207], v[78:81]
	v_mfma_f32_16x16x32_bf16 v[74:77], v[180:183], v[204:207], v[74:77]
	v_mfma_f32_16x16x32_bf16 v[70:73], v[172:175], v[212:215], v[70:73]
	s_setprio 0
	v_mfma_f32_16x16x32_bf16 v[66:69], v[180:183], v[212:215], v[66:69]
	s_barrier
	s_add_i32 s60, s60, s29
	v_lshl_add_u64 v[148:149], s[26:27], 0, v[0:1]
	s_mov_b32 m0, s60
	ds_read_b128 v[184:187], v143 offset:16384
	ds_read_b128 v[188:191], v143 offset:17408
	ds_read_b128 v[192:195], v143 offset:18432
	ds_read_b128 v[196:199], v143 offset:19456
	ds_read_b128 v[200:203], v143 offset:20480
	ds_read_b128 v[204:207], v143 offset:21504
	ds_read_b128 v[208:211], v143 offset:22528
	ds_read_b128 v[212:215], v143 offset:23552
	global_load_lds_dwordx4 v[148:149], off
	s_add_i32 m0, s60, 0x2000
	s_add_u32 s60, s26, 0x40000
	v_lshl_add_u64 v[150:151], s[26:27], 0, v[130:131]
	s_addc_u32 s61, s27, 0
	s_add_i32 s9, s9, s29
	global_load_lds_dwordx4 v[150:151], off
	v_lshl_add_u64 v[216:217], s[60:61], 0, v[0:1]
	s_mov_b32 m0, s9
	v_lshl_add_u64 v[218:219], s[38:39], 0, v[132:133]
	global_load_lds_dwordx4 v[216:217], off
	s_add_i32 m0, s9, 0x2000
	v_lshl_add_u64 v[216:217], s[60:61], 0, v[130:131]
	global_load_lds_dwordx4 v[216:217], off
	s_mov_b32 m0, s40
	v_lshl_add_u64 v[216:217], s[38:39], 0, v[134:135]
	global_load_lds_dwordx4 v[216:217], off
	s_mov_b32 m0, s41
	s_nop 0
	global_load_lds_dwordx4 v[218:219], off
	s_waitcnt vmcnt(8)
	s_waitcnt lgkmcnt(0)
	s_setprio 1
	s_barrier
	v_mfma_f32_16x16x32_bf16 v[62:65], v[144:147], v[184:187], v[62:65]
	v_mfma_f32_16x16x32_bf16 v[58:61], v[160:163], v[184:187], v[58:61]
	v_mfma_f32_16x16x32_bf16 v[54:57], v[144:147], v[192:195], v[54:57]
	v_mfma_f32_16x16x32_bf16 v[50:53], v[160:163], v[192:195], v[50:53]
	v_mfma_f32_16x16x32_bf16 v[38:41], v[144:147], v[200:203], v[38:41]
	v_mfma_f32_16x16x32_bf16 v[34:37], v[160:163], v[200:203], v[34:37]
	v_mfma_f32_16x16x32_bf16 v[22:25], v[144:147], v[208:211], v[22:25]
	v_mfma_f32_16x16x32_bf16 v[18:21], v[160:163], v[208:211], v[18:21]
	v_mfma_f32_16x16x32_bf16 v[62:65], v[156:159], v[188:191], v[62:65]
	v_mfma_f32_16x16x32_bf16 v[58:61], v[164:167], v[188:191], v[58:61]
	v_mfma_f32_16x16x32_bf16 v[54:57], v[156:159], v[196:199], v[54:57]
	v_mfma_f32_16x16x32_bf16 v[50:53], v[164:167], v[196:199], v[50:53]
	v_mfma_f32_16x16x32_bf16 v[38:41], v[156:159], v[204:207], v[38:41]
	v_mfma_f32_16x16x32_bf16 v[34:37], v[164:167], v[204:207], v[34:37]
	v_mfma_f32_16x16x32_bf16 v[22:25], v[156:159], v[212:215], v[22:25]
	v_mfma_f32_16x16x32_bf16 v[18:21], v[164:167], v[212:215], v[18:21]
	v_mfma_f32_16x16x32_bf16 v[46:49], v[168:171], v[184:187], v[46:49]
	v_mfma_f32_16x16x32_bf16 v[42:45], v[176:179], v[184:187], v[42:45]
	v_mfma_f32_16x16x32_bf16 v[30:33], v[168:171], v[192:195], v[30:33]
	v_mfma_f32_16x16x32_bf16 v[26:29], v[176:179], v[192:195], v[26:29]
	v_mfma_f32_16x16x32_bf16 v[14:17], v[168:171], v[200:203], v[14:17]
	v_mfma_f32_16x16x32_bf16 v[10:13], v[176:179], v[200:203], v[10:13]
	v_mfma_f32_16x16x32_bf16 v[6:9], v[168:171], v[208:211], v[6:9]
	v_mfma_f32_16x16x32_bf16 v[2:5], v[176:179], v[208:211], v[2:5]
	v_mfma_f32_16x16x32_bf16 v[46:49], v[172:175], v[188:191], v[46:49]
	v_mfma_f32_16x16x32_bf16 v[42:45], v[180:183], v[188:191], v[42:45]
	v_mfma_f32_16x16x32_bf16 v[30:33], v[172:175], v[196:199], v[30:33]
	v_mfma_f32_16x16x32_bf16 v[26:29], v[180:183], v[196:199], v[26:29]
	v_mfma_f32_16x16x32_bf16 v[14:17], v[172:175], v[204:207], v[14:17]
	v_mfma_f32_16x16x32_bf16 v[10:13], v[180:183], v[204:207], v[10:13]
	v_mfma_f32_16x16x32_bf16 v[6:9], v[172:175], v[212:215], v[6:9]
	s_setprio 0
	v_mfma_f32_16x16x32_bf16 v[2:5], v[180:183], v[212:215], v[2:5]
	s_barrier
	s_add_i32 s9, 0, 0x18000
	s_add_i32 s60, 0, 0x1c000
	v_add_u32_e32 v164, s9, v141
	v_add_u32_e32 v180, s60, v141
	ds_read_b128 v[144:147], v164
	ds_read_b128 v[156:159], v164 offset:1024
	ds_read_b128 v[160:163], v164 offset:2048
	ds_read_b128 v[164:167], v164 offset:3072
	ds_read_b128 v[168:171], v180
	ds_read_b128 v[172:175], v180 offset:1024
	ds_read_b128 v[176:179], v180 offset:2048
	ds_read_b128 v[180:183], v180 offset:3072
	s_add_u32 s38, s38, 0x40000
	s_addc_u32 s39, s39, 0
	s_mov_b32 m0, s42
	v_lshl_add_u64 v[220:221], s[38:39], 0, v[134:135]
	ds_read_b128 v[184:187], v143 offset:32768
	ds_read_b128 v[188:191], v143 offset:33792
	ds_read_b128 v[192:195], v143 offset:34816
	ds_read_b128 v[196:199], v143 offset:35840
	ds_read_b128 v[200:203], v143 offset:36864
	ds_read_b128 v[204:207], v143 offset:37888
	ds_read_b128 v[208:211], v143 offset:38912
	ds_read_b128 v[212:215], v143 offset:39936
	global_load_lds_dwordx4 v[220:221], off
	s_mov_b32 m0, s43
	v_lshl_add_u64 v[220:221], s[38:39], 0, v[132:133]
	global_load_lds_dwordx4 v[220:221], off
	s_waitcnt vmcnt(8)
	s_waitcnt lgkmcnt(0)
	s_setprio 1
	s_barrier
	v_mfma_f32_16x16x32_bf16 v[126:129], v[144:147], v[184:187], v[126:129]
	v_mfma_f32_16x16x32_bf16 v[122:125], v[160:163], v[184:187], v[122:125]
	v_mfma_f32_16x16x32_bf16 v[118:121], v[144:147], v[192:195], v[118:121]
	v_mfma_f32_16x16x32_bf16 v[114:117], v[160:163], v[192:195], v[114:117]
	v_mfma_f32_16x16x32_bf16 v[102:105], v[144:147], v[200:203], v[102:105]
	v_mfma_f32_16x16x32_bf16 v[98:101], v[160:163], v[200:203], v[98:101]
	v_mfma_f32_16x16x32_bf16 v[86:89], v[144:147], v[208:211], v[86:89]
	v_mfma_f32_16x16x32_bf16 v[82:85], v[160:163], v[208:211], v[82:85]
	v_mfma_f32_16x16x32_bf16 v[126:129], v[156:159], v[188:191], v[126:129]
	v_mfma_f32_16x16x32_bf16 v[122:125], v[164:167], v[188:191], v[122:125]
	v_mfma_f32_16x16x32_bf16 v[118:121], v[156:159], v[196:199], v[118:121]
	v_mfma_f32_16x16x32_bf16 v[114:117], v[164:167], v[196:199], v[114:117]
	v_mfma_f32_16x16x32_bf16 v[102:105], v[156:159], v[204:207], v[102:105]
	v_mfma_f32_16x16x32_bf16 v[98:101], v[164:167], v[204:207], v[98:101]
	v_mfma_f32_16x16x32_bf16 v[86:89], v[156:159], v[212:215], v[86:89]
	v_mfma_f32_16x16x32_bf16 v[82:85], v[164:167], v[212:215], v[82:85]
	v_mfma_f32_16x16x32_bf16 v[110:113], v[168:171], v[184:187], v[110:113]
	v_mfma_f32_16x16x32_bf16 v[106:109], v[176:179], v[184:187], v[106:109]
	v_mfma_f32_16x16x32_bf16 v[94:97], v[168:171], v[192:195], v[94:97]
	v_mfma_f32_16x16x32_bf16 v[90:93], v[176:179], v[192:195], v[90:93]
	v_mfma_f32_16x16x32_bf16 v[78:81], v[168:171], v[200:203], v[78:81]
	v_mfma_f32_16x16x32_bf16 v[74:77], v[176:179], v[200:203], v[74:77]
	v_mfma_f32_16x16x32_bf16 v[70:73], v[168:171], v[208:211], v[70:73]
	v_mfma_f32_16x16x32_bf16 v[66:69], v[176:179], v[208:211], v[66:69]
	v_mfma_f32_16x16x32_bf16 v[110:113], v[172:175], v[188:191], v[110:113]
	v_mfma_f32_16x16x32_bf16 v[106:109], v[180:183], v[188:191], v[106:109]
	v_mfma_f32_16x16x32_bf16 v[94:97], v[172:175], v[196:199], v[94:97]
	v_mfma_f32_16x16x32_bf16 v[90:93], v[180:183], v[196:199], v[90:93]
	v_mfma_f32_16x16x32_bf16 v[78:81], v[172:175], v[204:207], v[78:81]
	v_mfma_f32_16x16x32_bf16 v[74:77], v[180:183], v[204:207], v[74:77]
	v_mfma_f32_16x16x32_bf16 v[70:73], v[172:175], v[212:215], v[70:73]
	s_setprio 0
	v_mfma_f32_16x16x32_bf16 v[66:69], v[180:183], v[212:215], v[66:69]
	s_barrier
	s_add_i32 s9, s9, s29
	v_lshl_add_u64 v[148:149], v[148:149], 0, s[70:71]
	s_mov_b32 m0, s9
	ds_read_b128 v[184:187], v143 offset:49152
	ds_read_b128 v[188:191], v143 offset:50176
	ds_read_b128 v[192:195], v143 offset:51200
	ds_read_b128 v[196:199], v143 offset:52224
	ds_read_b128 v[200:203], v143 offset:53248
	ds_read_b128 v[204:207], v143 offset:54272
	ds_read_b128 v[208:211], v143 offset:55296
	ds_read_b128 v[212:215], v143 offset:56320
	global_load_lds_dwordx4 v[148:149], off
	s_add_i32 m0, s9, 0x2000
	s_add_u32 s26, s26, 0x40080
	v_lshl_add_u64 v[148:149], v[150:151], 0, s[70:71]
	s_addc_u32 s27, s27, 0
	s_add_i32 s9, s60, s29
	global_load_lds_dwordx4 v[148:149], off
	s_mov_b32 m0, s9
	v_lshl_add_u64 v[148:149], s[26:27], 0, v[0:1]
	global_load_lds_dwordx4 v[148:149], off
	s_add_i32 m0, s9, 0x2000
	v_lshl_add_u64 v[148:149], s[26:27], 0, v[130:131]
	global_load_lds_dwordx4 v[148:149], off
	s_mov_b32 m0, s44
	v_lshl_add_u64 v[148:149], v[216:217], 0, s[70:71]
	global_load_lds_dwordx4 v[148:149], off
	s_mov_b32 m0, s45
	v_lshl_add_u64 v[148:149], v[218:219], 0, s[70:71]
	global_load_lds_dwordx4 v[148:149], off
	s_waitcnt vmcnt(8)
	s_waitcnt lgkmcnt(0)
	s_setprio 1
	s_barrier
	v_mfma_f32_16x16x32_bf16 v[62:65], v[144:147], v[184:187], v[62:65]
	v_mfma_f32_16x16x32_bf16 v[58:61], v[160:163], v[184:187], v[58:61]
	v_mfma_f32_16x16x32_bf16 v[54:57], v[144:147], v[192:195], v[54:57]
	v_mfma_f32_16x16x32_bf16 v[50:53], v[160:163], v[192:195], v[50:53]
	v_mfma_f32_16x16x32_bf16 v[38:41], v[144:147], v[200:203], v[38:41]
	v_mfma_f32_16x16x32_bf16 v[34:37], v[160:163], v[200:203], v[34:37]
	v_mfma_f32_16x16x32_bf16 v[22:25], v[144:147], v[208:211], v[22:25]
	v_mfma_f32_16x16x32_bf16 v[18:21], v[160:163], v[208:211], v[18:21]
	v_mfma_f32_16x16x32_bf16 v[62:65], v[156:159], v[188:191], v[62:65]
	v_mfma_f32_16x16x32_bf16 v[58:61], v[164:167], v[188:191], v[58:61]
	v_mfma_f32_16x16x32_bf16 v[54:57], v[156:159], v[196:199], v[54:57]
	v_mfma_f32_16x16x32_bf16 v[50:53], v[164:167], v[196:199], v[50:53]
	v_mfma_f32_16x16x32_bf16 v[38:41], v[156:159], v[204:207], v[38:41]
	v_mfma_f32_16x16x32_bf16 v[34:37], v[164:167], v[204:207], v[34:37]
	v_mfma_f32_16x16x32_bf16 v[22:25], v[156:159], v[212:215], v[22:25]
	v_mfma_f32_16x16x32_bf16 v[18:21], v[164:167], v[212:215], v[18:21]
	v_mfma_f32_16x16x32_bf16 v[46:49], v[168:171], v[184:187], v[46:49]
	v_mfma_f32_16x16x32_bf16 v[42:45], v[176:179], v[184:187], v[42:45]
	v_mfma_f32_16x16x32_bf16 v[30:33], v[168:171], v[192:195], v[30:33]
	v_mfma_f32_16x16x32_bf16 v[26:29], v[176:179], v[192:195], v[26:29]
	v_mfma_f32_16x16x32_bf16 v[14:17], v[168:171], v[200:203], v[14:17]
	v_mfma_f32_16x16x32_bf16 v[10:13], v[176:179], v[200:203], v[10:13]
	v_mfma_f32_16x16x32_bf16 v[6:9], v[168:171], v[208:211], v[6:9]
	v_mfma_f32_16x16x32_bf16 v[2:5], v[176:179], v[208:211], v[2:5]
	v_mfma_f32_16x16x32_bf16 v[46:49], v[172:175], v[188:191], v[46:49]
	v_mfma_f32_16x16x32_bf16 v[42:45], v[180:183], v[188:191], v[42:45]
	v_mfma_f32_16x16x32_bf16 v[30:33], v[172:175], v[196:199], v[30:33]
	v_mfma_f32_16x16x32_bf16 v[26:29], v[180:183], v[196:199], v[26:29]
	v_mfma_f32_16x16x32_bf16 v[14:17], v[172:175], v[204:207], v[14:17]
	v_mfma_f32_16x16x32_bf16 v[10:13], v[180:183], v[204:207], v[10:13]
	v_mfma_f32_16x16x32_bf16 v[6:9], v[172:175], v[212:215], v[6:9]
	s_setprio 0
	v_mfma_f32_16x16x32_bf16 v[2:5], v[180:183], v[212:215], v[2:5]
	s_barrier
	s_add_i32 s53, s53, 2
	s_add_u32 s36, s36, 0x100
	s_addc_u32 s37, s37, 0
	s_add_u32 s51, s51, 0x100
	s_addc_u32 s52, s52, 0
	s_cmp_gt_u32 s53, 13
	s_cbranch_scc0 .LBB0_220
	s_and_b64 vcc, exec, s[14:15]
	s_cbranch_vccz .LBB0_223
	s_barrier

.LBB0_376:
	s_add_u32 s53, s18, s9
	s_addc_u32 s74, s19, 0
	s_add_u32 s60, s53, 0x100
	s_addc_u32 s61, s74, 0
	s_and_b64 s[26:27], s[38:39], exec
	s_cselect_b32 s61, s25, s61
	s_cselect_b32 s60, s24, s60
	s_add_u32 s9, s16, s9
	s_addc_u32 s26, s17, 0
	s_add_u32 s9, s9, 0x100
	s_addc_u32 s72, s26, 0
	s_add_i32 s92, 0, 0x10000
	s_and_b64 s[26:27], s[38:39], exec
	s_cselect_b32 s73, s23, s72
	s_cselect_b32 s72, s52, s9
	s_add_i32 s39, 0, 0x14000
	s_add_u32 vcc_lo, s53, 0x58080
	s_addc_u32 vcc_hi, s74, 0
	s_add_i32 s78, s92, s41
	s_add_i32 m0, s42, 0xc000
	s_add_i32 s93, s42, 0xe000
	s_add_i32 s91, s78, 0x2000
	v_add_u32_e32 v148, s92, v137
	s_add_u32 s74, s72, 0x10000
	ds_read_b128 v[140:143], v148
	ds_read_b128 v[144:147], v148 offset:1024
	ds_read_b128 v[156:159], v148 offset:2048
	ds_read_b128 v[160:163], v148 offset:3072
	v_add_u32_e32 v148, s39, v137
	s_addc_u32 s75, s73, 0
	s_add_i32 s79, s39, s41
	ds_read_b128 v[164:167], v148
	ds_read_b128 v[168:171], v148 offset:1024
	ds_read_b128 v[172:175], v148 offset:2048
	ds_read_b128 v[176:179], v148 offset:3072
	s_add_i32 s90, s79, 0x2000
	s_add_i32 s97, 0, 0x18000
	s_add_i32 s83, 0, 0x1c000
	s_add_u32 s26, s60, 0x58000
	s_addc_u32 s27, s61, 0
	s_add_i32 s53, s97, s41
	s_add_i32 s9, s53, 0x2000
	s_add_u32 s38, s72, 0x10080
	s_addc_u32 s39, s73, 0
	s_add_i32 s96, s83, s41
	s_add_i32 s92, s96, 0x2000
	v_lshl_add_u64 v[148:149], vcc, 0, v[134:135]
	ds_read_b128 v[180:183], v139
	ds_read_b128 v[184:187], v139 offset:1024
	ds_read_b128 v[188:191], v139 offset:2048
	ds_read_b128 v[192:195], v139 offset:3072
	ds_read_b128 v[196:199], v139 offset:4096
	ds_read_b128 v[200:203], v139 offset:5120
	ds_read_b128 v[204:207], v139 offset:6144
	ds_read_b128 v[208:211], v139 offset:7168
	global_load_lds_dwordx4 v[148:149], off
	s_mov_b32 m0, s93
	v_lshl_add_u64 v[148:149], vcc, 0, v[132:133]
	global_load_lds_dwordx4 v[148:149], off
	s_waitcnt vmcnt(8)
	s_waitcnt lgkmcnt(0)
	s_setprio 1
	s_barrier
	v_mfma_f32_16x16x32_bf16 v[126:129], v[140:143], v[180:183], v[126:129]
	v_mfma_f32_16x16x32_bf16 v[122:125], v[156:159], v[180:183], v[122:125]
	v_mfma_f32_16x16x32_bf16 v[118:121], v[140:143], v[188:191], v[118:121]
	v_mfma_f32_16x16x32_bf16 v[114:117], v[156:159], v[188:191], v[114:117]
	v_mfma_f32_16x16x32_bf16 v[102:105], v[140:143], v[196:199], v[102:105]
	v_mfma_f32_16x16x32_bf16 v[98:101], v[156:159], v[196:199], v[98:101]
	v_mfma_f32_16x16x32_bf16 v[86:89], v[140:143], v[204:207], v[86:89]
	v_mfma_f32_16x16x32_bf16 v[82:85], v[156:159], v[204:207], v[82:85]
	v_mfma_f32_16x16x32_bf16 v[126:129], v[144:147], v[184:187], v[126:129]
	v_mfma_f32_16x16x32_bf16 v[122:125], v[160:163], v[184:187], v[122:125]
	v_mfma_f32_16x16x32_bf16 v[118:121], v[144:147], v[192:195], v[118:121]
	v_mfma_f32_16x16x32_bf16 v[114:117], v[160:163], v[192:195], v[114:117]
	v_mfma_f32_16x16x32_bf16 v[102:105], v[144:147], v[200:203], v[102:105]
	v_mfma_f32_16x16x32_bf16 v[98:101], v[160:163], v[200:203], v[98:101]
	v_mfma_f32_16x16x32_bf16 v[86:89], v[144:147], v[208:211], v[86:89]
	v_mfma_f32_16x16x32_bf16 v[82:85], v[160:163], v[208:211], v[82:85]
	v_mfma_f32_16x16x32_bf16 v[110:113], v[164:167], v[180:183], v[110:113]
	v_mfma_f32_16x16x32_bf16 v[106:109], v[172:175], v[180:183], v[106:109]
	v_mfma_f32_16x16x32_bf16 v[94:97], v[164:167], v[188:191], v[94:97]
	v_mfma_f32_16x16x32_bf16 v[90:93], v[172:175], v[188:191], v[90:93]
	v_mfma_f32_16x16x32_bf16 v[78:81], v[164:167], v[196:199], v[78:81]
	v_mfma_f32_16x16x32_bf16 v[74:77], v[172:175], v[196:199], v[74:77]
	v_mfma_f32_16x16x32_bf16 v[70:73], v[164:167], v[204:207], v[70:73]
	v_mfma_f32_16x16x32_bf16 v[66:69], v[172:175], v[204:207], v[66:69]
	v_mfma_f32_16x16x32_bf16 v[110:113], v[168:171], v[184:187], v[110:113]
	v_mfma_f32_16x16x32_bf16 v[106:109], v[176:179], v[184:187], v[106:109]
	v_mfma_f32_16x16x32_bf16 v[94:97], v[168:171], v[192:195], v[94:97]
	v_mfma_f32_16x16x32_bf16 v[90:93], v[176:179], v[192:195], v[90:93]
	v_mfma_f32_16x16x32_bf16 v[78:81], v[168:171], v[200:203], v[78:81]
	v_mfma_f32_16x16x32_bf16 v[74:77], v[176:179], v[200:203], v[74:77]
	v_mfma_f32_16x16x32_bf16 v[70:73], v[168:171], v[208:211], v[70:73]
	s_setprio 0
	v_mfma_f32_16x16x32_bf16 v[66:69], v[176:179], v[208:211], v[66:69]
	s_barrier
	s_mov_b32 m0, s78
	v_lshl_add_u64 v[148:149], s[72:73], 0, v[0:1]
	ds_read_b128 v[180:183], v139 offset:16384
	ds_read_b128 v[184:187], v139 offset:17408
	ds_read_b128 v[188:191], v139 offset:18432
	ds_read_b128 v[192:195], v139 offset:19456
	ds_read_b128 v[196:199], v139 offset:20480
	ds_read_b128 v[200:203], v139 offset:21504
	ds_read_b128 v[204:207], v139 offset:22528
	ds_read_b128 v[208:211], v139 offset:23552
	global_load_lds_dwordx4 v[148:149], off
	v_lshl_add_u64 v[150:151], s[72:73], 0, v[130:131]
	s_mov_b32 m0, s91
	v_lshl_add_u64 v[212:213], s[74:75], 0, v[0:1]
	global_load_lds_dwordx4 v[150:151], off
	s_mov_b32 m0, s79
	v_lshl_add_u64 v[214:215], s[60:61], 0, v[132:133]
	global_load_lds_dwordx4 v[212:213], off
	s_mov_b32 m0, s90
	v_lshl_add_u64 v[212:213], s[74:75], 0, v[130:131]
	global_load_lds_dwordx4 v[212:213], off
	s_mov_b32 m0, s42
	v_lshl_add_u64 v[212:213], s[60:61], 0, v[134:135]
	global_load_lds_dwordx4 v[212:213], off
	s_mov_b32 m0, s43
	s_nop 0
	global_load_lds_dwordx4 v[214:215], off
	s_waitcnt vmcnt(8)
	s_waitcnt lgkmcnt(0)
	s_setprio 1
	s_barrier
	v_mfma_f32_16x16x32_bf16 v[62:65], v[140:143], v[180:183], v[62:65]
	v_mfma_f32_16x16x32_bf16 v[58:61], v[156:159], v[180:183], v[58:61]
	v_mfma_f32_16x16x32_bf16 v[54:57], v[140:143], v[188:191], v[54:57]
	v_mfma_f32_16x16x32_bf16 v[50:53], v[156:159], v[188:191], v[50:53]
	v_mfma_f32_16x16x32_bf16 v[38:41], v[140:143], v[196:199], v[38:41]
	v_mfma_f32_16x16x32_bf16 v[34:37], v[156:159], v[196:199], v[34:37]
	v_mfma_f32_16x16x32_bf16 v[22:25], v[140:143], v[204:207], v[22:25]
	v_mfma_f32_16x16x32_bf16 v[18:21], v[156:159], v[204:207], v[18:21]
	v_mfma_f32_16x16x32_bf16 v[62:65], v[144:147], v[184:187], v[62:65]
	v_mfma_f32_16x16x32_bf16 v[58:61], v[160:163], v[184:187], v[58:61]
	v_mfma_f32_16x16x32_bf16 v[54:57], v[144:147], v[192:195], v[54:57]
	v_mfma_f32_16x16x32_bf16 v[50:53], v[160:163], v[192:195], v[50:53]
	v_mfma_f32_16x16x32_bf16 v[38:41], v[144:147], v[200:203], v[38:41]
	v_mfma_f32_16x16x32_bf16 v[34:37], v[160:163], v[200:203], v[34:37]
	v_mfma_f32_16x16x32_bf16 v[22:25], v[144:147], v[208:211], v[22:25]
	v_mfma_f32_16x16x32_bf16 v[18:21], v[160:163], v[208:211], v[18:21]
	v_mfma_f32_16x16x32_bf16 v[46:49], v[164:167], v[180:183], v[46:49]
	v_mfma_f32_16x16x32_bf16 v[42:45], v[172:175], v[180:183], v[42:45]
	v_mfma_f32_16x16x32_bf16 v[30:33], v[164:167], v[188:191], v[30:33]
	v_mfma_f32_16x16x32_bf16 v[26:29], v[172:175], v[188:191], v[26:29]
	v_mfma_f32_16x16x32_bf16 v[14:17], v[164:167], v[196:199], v[14:17]
	v_mfma_f32_16x16x32_bf16 v[10:13], v[172:175], v[196:199], v[10:13]
	v_mfma_f32_16x16x32_bf16 v[6:9], v[164:167], v[204:207], v[6:9]
	v_mfma_f32_16x16x32_bf16 v[2:5], v[172:175], v[204:207], v[2:5]
	v_mfma_f32_16x16x32_bf16 v[46:49], v[168:171], v[184:187], v[46:49]
	v_mfma_f32_16x16x32_bf16 v[42:45], v[176:179], v[184:187], v[42:45]
	v_mfma_f32_16x16x32_bf16 v[30:33], v[168:171], v[192:195], v[30:33]
	v_mfma_f32_16x16x32_bf16 v[26:29], v[176:179], v[192:195], v[26:29]
	v_mfma_f32_16x16x32_bf16 v[14:17], v[168:171], v[200:203], v[14:17]
	v_mfma_f32_16x16x32_bf16 v[10:13], v[176:179], v[200:203], v[10:13]
	v_mfma_f32_16x16x32_bf16 v[6:9], v[168:171], v[208:211], v[6:9]
	s_setprio 0
	v_mfma_f32_16x16x32_bf16 v[2:5], v[176:179], v[208:211], v[2:5]
	s_barrier
	v_add_u32_e32 v160, s97, v137
	v_add_u32_e32 v176, s83, v137
	ds_read_b128 v[140:143], v160
	ds_read_b128 v[144:147], v160 offset:1024
	ds_read_b128 v[156:159], v160 offset:2048
	ds_read_b128 v[160:163], v160 offset:3072
	ds_read_b128 v[164:167], v176
	ds_read_b128 v[168:171], v176 offset:1024
	ds_read_b128 v[172:175], v176 offset:2048
	ds_read_b128 v[176:179], v176 offset:3072
	s_mov_b32 m0, s44
	v_lshl_add_u64 v[216:217], s[26:27], 0, v[134:135]
	ds_read_b128 v[180:183], v139 offset:32768
	ds_read_b128 v[184:187], v139 offset:33792
	ds_read_b128 v[188:191], v139 offset:34816
	ds_read_b128 v[192:195], v139 offset:35840
	ds_read_b128 v[196:199], v139 offset:36864
	ds_read_b128 v[200:203], v139 offset:37888
	ds_read_b128 v[204:207], v139 offset:38912
	ds_read_b128 v[208:211], v139 offset:39936
	global_load_lds_dwordx4 v[216:217], off
	s_mov_b32 m0, s45
	v_lshl_add_u64 v[216:217], s[26:27], 0, v[132:133]
	global_load_lds_dwordx4 v[216:217], off
	s_waitcnt vmcnt(8)
	s_waitcnt lgkmcnt(0)
	s_setprio 1
	s_barrier
	v_mfma_f32_16x16x32_bf16 v[126:129], v[140:143], v[180:183], v[126:129]
	v_mfma_f32_16x16x32_bf16 v[122:125], v[156:159], v[180:183], v[122:125]
	v_mfma_f32_16x16x32_bf16 v[118:121], v[140:143], v[188:191], v[118:121]
	v_mfma_f32_16x16x32_bf16 v[114:117], v[156:159], v[188:191], v[114:117]
	v_mfma_f32_16x16x32_bf16 v[102:105], v[140:143], v[196:199], v[102:105]
	v_mfma_f32_16x16x32_bf16 v[98:101], v[156:159], v[196:199], v[98:101]
	v_mfma_f32_16x16x32_bf16 v[86:89], v[140:143], v[204:207], v[86:89]
	v_mfma_f32_16x16x32_bf16 v[82:85], v[156:159], v[204:207], v[82:85]
	v_mfma_f32_16x16x32_bf16 v[126:129], v[144:147], v[184:187], v[126:129]
	v_mfma_f32_16x16x32_bf16 v[122:125], v[160:163], v[184:187], v[122:125]
	v_mfma_f32_16x16x32_bf16 v[118:121], v[144:147], v[192:195], v[118:121]
	v_mfma_f32_16x16x32_bf16 v[114:117], v[160:163], v[192:195], v[114:117]
	v_mfma_f32_16x16x32_bf16 v[102:105], v[144:147], v[200:203], v[102:105]
	v_mfma_f32_16x16x32_bf16 v[98:101], v[160:163], v[200:203], v[98:101]
	v_mfma_f32_16x16x32_bf16 v[86:89], v[144:147], v[208:211], v[86:89]
	v_mfma_f32_16x16x32_bf16 v[82:85], v[160:163], v[208:211], v[82:85]
	v_mfma_f32_16x16x32_bf16 v[110:113], v[164:167], v[180:183], v[110:113]
	v_mfma_f32_16x16x32_bf16 v[106:109], v[172:175], v[180:183], v[106:109]
	v_mfma_f32_16x16x32_bf16 v[94:97], v[164:167], v[188:191], v[94:97]
	v_mfma_f32_16x16x32_bf16 v[90:93], v[172:175], v[188:191], v[90:93]
	v_mfma_f32_16x16x32_bf16 v[78:81], v[164:167], v[196:199], v[78:81]
	v_mfma_f32_16x16x32_bf16 v[74:77], v[172:175], v[196:199], v[74:77]
	v_mfma_f32_16x16x32_bf16 v[70:73], v[164:167], v[204:207], v[70:73]
	v_mfma_f32_16x16x32_bf16 v[66:69], v[172:175], v[204:207], v[66:69]
	v_mfma_f32_16x16x32_bf16 v[110:113], v[168:171], v[184:187], v[110:113]
	v_mfma_f32_16x16x32_bf16 v[106:109], v[176:179], v[184:187], v[106:109]
	v_mfma_f32_16x16x32_bf16 v[94:97], v[168:171], v[192:195], v[94:97]
	v_mfma_f32_16x16x32_bf16 v[90:93], v[176:179], v[192:195], v[90:93]
	v_mfma_f32_16x16x32_bf16 v[78:81], v[168:171], v[200:203], v[78:81]
	v_mfma_f32_16x16x32_bf16 v[74:77], v[176:179], v[200:203], v[74:77]
	v_mfma_f32_16x16x32_bf16 v[70:73], v[168:171], v[208:211], v[70:73]
	s_setprio 0
	v_mfma_f32_16x16x32_bf16 v[66:69], v[176:179], v[208:211], v[66:69]
	s_barrier
	s_mov_b32 m0, s53
	v_lshl_add_u64 v[148:149], v[148:149], 0, s[70:71]
	ds_read_b128 v[180:183], v139 offset:49152
	ds_read_b128 v[184:187], v139 offset:50176
	ds_read_b128 v[188:191], v139 offset:51200
	ds_read_b128 v[192:195], v139 offset:52224
	ds_read_b128 v[196:199], v139 offset:53248
	ds_read_b128 v[200:203], v139 offset:54272
	ds_read_b128 v[204:207], v139 offset:55296
	ds_read_b128 v[208:211], v139 offset:56320
	global_load_lds_dwordx4 v[148:149], off
	s_mov_b32 m0, s9
	v_lshl_add_u64 v[148:149], v[150:151], 0, s[70:71]
	global_load_lds_dwordx4 v[148:149], off
	s_mov_b32 m0, s96
	v_lshl_add_u64 v[148:149], s[38:39], 0, v[0:1]
	global_load_lds_dwordx4 v[148:149], off
	s_mov_b32 m0, s92
	v_lshl_add_u64 v[148:149], s[38:39], 0, v[130:131]
	global_load_lds_dwordx4 v[148:149], off
	s_mov_b32 m0, s46
	v_lshl_add_u64 v[148:149], v[212:213], 0, s[70:71]
	global_load_lds_dwordx4 v[148:149], off
	s_mov_b32 m0, s47
	v_lshl_add_u64 v[148:149], v[214:215], 0, s[70:71]
	global_load_lds_dwordx4 v[148:149], off
	s_waitcnt vmcnt(8)
	s_waitcnt lgkmcnt(0)
	s_setprio 1
	s_barrier
	v_mfma_f32_16x16x32_bf16 v[62:65], v[140:143], v[180:183], v[62:65]
	v_mfma_f32_16x16x32_bf16 v[58:61], v[156:159], v[180:183], v[58:61]
	v_mfma_f32_16x16x32_bf16 v[54:57], v[140:143], v[188:191], v[54:57]
	v_mfma_f32_16x16x32_bf16 v[50:53], v[156:159], v[188:191], v[50:53]
	v_mfma_f32_16x16x32_bf16 v[38:41], v[140:143], v[196:199], v[38:41]
	v_mfma_f32_16x16x32_bf16 v[34:37], v[156:159], v[196:199], v[34:37]
	v_mfma_f32_16x16x32_bf16 v[22:25], v[140:143], v[204:207], v[22:25]
	v_mfma_f32_16x16x32_bf16 v[18:21], v[156:159], v[204:207], v[18:21]
	v_mfma_f32_16x16x32_bf16 v[62:65], v[144:147], v[184:187], v[62:65]
	v_mfma_f32_16x16x32_bf16 v[58:61], v[160:163], v[184:187], v[58:61]
	v_mfma_f32_16x16x32_bf16 v[54:57], v[144:147], v[192:195], v[54:57]
	v_mfma_f32_16x16x32_bf16 v[50:53], v[160:163], v[192:195], v[50:53]
	v_mfma_f32_16x16x32_bf16 v[38:41], v[144:147], v[200:203], v[38:41]
	v_mfma_f32_16x16x32_bf16 v[34:37], v[160:163], v[200:203], v[34:37]
	v_mfma_f32_16x16x32_bf16 v[22:25], v[144:147], v[208:211], v[22:25]
	v_mfma_f32_16x16x32_bf16 v[18:21], v[160:163], v[208:211], v[18:21]
	v_mfma_f32_16x16x32_bf16 v[46:49], v[164:167], v[180:183], v[46:49]
	v_mfma_f32_16x16x32_bf16 v[42:45], v[172:175], v[180:183], v[42:45]
	v_mfma_f32_16x16x32_bf16 v[30:33], v[164:167], v[188:191], v[30:33]
	v_mfma_f32_16x16x32_bf16 v[26:29], v[172:175], v[188:191], v[26:29]
	v_mfma_f32_16x16x32_bf16 v[14:17], v[164:167], v[196:199], v[14:17]
	v_mfma_f32_16x16x32_bf16 v[10:13], v[172:175], v[196:199], v[10:13]
	v_mfma_f32_16x16x32_bf16 v[6:9], v[164:167], v[204:207], v[6:9]
	v_mfma_f32_16x16x32_bf16 v[2:5], v[172:175], v[204:207], v[2:5]
	v_mfma_f32_16x16x32_bf16 v[46:49], v[168:171], v[184:187], v[46:49]
	v_mfma_f32_16x16x32_bf16 v[42:45], v[176:179], v[184:187], v[42:45]
	v_mfma_f32_16x16x32_bf16 v[30:33], v[168:171], v[192:195], v[30:33]
	v_mfma_f32_16x16x32_bf16 v[26:29], v[176:179], v[192:195], v[26:29]
	v_mfma_f32_16x16x32_bf16 v[14:17], v[168:171], v[200:203], v[14:17]
	v_mfma_f32_16x16x32_bf16 v[10:13], v[176:179], v[200:203], v[10:13]
	v_mfma_f32_16x16x32_bf16 v[6:9], v[168:171], v[208:211], v[6:9]
	s_setprio 0
	v_mfma_f32_16x16x32_bf16 v[2:5], v[176:179], v[208:211], v[2:5]
	s_barrier
	s_movk_i32 s9, 0x100
	s_andn2_b64 vcc, exec, s[4:5]
	s_mov_b64 s[38:39], -1
	s_mov_b64 s[4:5], 0
	s_cbranch_vccz .LBB0_376
	s_and_b64 vcc, exec, s[14:15]
	s_cbranch_vccz .LBB0_379
	s_barrier

.LBB0_393:
	s_ashr_i32 s19, s18, 31
	s_lshl_b64 s[24:25], s[18:19], 16
	s_add_u32 s24, s29, s24
	s_addc_u32 s25, s38, s25
	s_and_b64 s[4:5], s[4:5], exec
	s_cselect_b32 s5, s25, s27
	s_cselect_b32 s4, s24, s26
	s_add_i32 s19, 0, 0x10000
	s_add_i32 s48, 0, 0x14000
	v_add_u32_e32 v14, s19, v137
	v_add_u32_e32 v30, s48, v137
	.p2align 6
	ds_read_b128 v[2:5], v14
	ds_read_b128 v[6:9], v14 offset:1024
	ds_read_b128 v[10:13], v14 offset:2048
	ds_read_b128 v[14:17], v14 offset:3072
	ds_read_b128 v[18:21], v30
	ds_read_b128 v[22:25], v30 offset:1024
	ds_read_b128 v[26:29], v30 offset:2048
	ds_read_b128 v[30:33], v30 offset:3072
	s_add_u32 s26, s36, 0x58080
	s_addc_u32 s27, s37, 0
	v_lshl_add_u64 v[66:67], s[26:27], 0, v[134:135]
	s_add_i32 m0, s40, 0xc000
	ds_read_b128 v[34:37], v139
	ds_read_b128 v[38:41], v139 offset:1024
	ds_read_b128 v[42:45], v139 offset:2048
	ds_read_b128 v[46:49], v139 offset:3072
	ds_read_b128 v[50:53], v139 offset:4096
	ds_read_b128 v[54:57], v139 offset:5120
	ds_read_b128 v[58:61], v139 offset:6144
	ds_read_b128 v[62:65], v139 offset:7168
	global_load_lds_dwordx4 v[66:67], off
	s_add_i32 m0, s40, 0xe000
	v_lshl_add_u64 v[66:67], s[26:27], 0, v[132:133]
	global_load_lds_dwordx4 v[66:67], off
	s_waitcnt vmcnt(8)
	s_waitcnt lgkmcnt(0)
	s_setprio 1
	s_barrier
	v_mfma_f32_16x16x32_bf16 v[66:69], v[2:5], v[34:37], 0
	v_mfma_f32_16x16x32_bf16 v[70:73], v[10:13], v[34:37], 0
	v_mfma_f32_16x16x32_bf16 v[74:77], v[2:5], v[42:45], 0
	v_mfma_f32_16x16x32_bf16 v[78:81], v[10:13], v[42:45], 0
	v_mfma_f32_16x16x32_bf16 v[82:85], v[2:5], v[50:53], 0
	v_mfma_f32_16x16x32_bf16 v[86:89], v[10:13], v[50:53], 0
	v_mfma_f32_16x16x32_bf16 v[90:93], v[2:5], v[58:61], 0
	v_mfma_f32_16x16x32_bf16 v[94:97], v[10:13], v[58:61], 0
	v_mfma_f32_16x16x32_bf16 v[66:69], v[6:9], v[38:41], v[66:69]
	v_mfma_f32_16x16x32_bf16 v[70:73], v[14:17], v[38:41], v[70:73]
	v_mfma_f32_16x16x32_bf16 v[74:77], v[6:9], v[46:49], v[74:77]
	v_mfma_f32_16x16x32_bf16 v[78:81], v[14:17], v[46:49], v[78:81]
	v_mfma_f32_16x16x32_bf16 v[82:85], v[6:9], v[54:57], v[82:85]
	v_mfma_f32_16x16x32_bf16 v[86:89], v[14:17], v[54:57], v[86:89]
	v_mfma_f32_16x16x32_bf16 v[90:93], v[6:9], v[62:65], v[90:93]
	v_mfma_f32_16x16x32_bf16 v[94:97], v[14:17], v[62:65], v[94:97]
	v_mfma_f32_16x16x32_bf16 v[98:101], v[18:21], v[34:37], 0
	v_mfma_f32_16x16x32_bf16 v[34:37], v[26:29], v[34:37], 0
	v_mfma_f32_16x16x32_bf16 v[98:101], v[22:25], v[38:41], v[98:101]
	v_mfma_f32_16x16x32_bf16 v[34:37], v[30:33], v[38:41], v[34:37]
	v_mfma_f32_16x16x32_bf16 v[38:41], v[18:21], v[42:45], 0
	v_mfma_f32_16x16x32_bf16 v[42:45], v[26:29], v[42:45], 0
	v_mfma_f32_16x16x32_bf16 v[102:105], v[30:33], v[46:49], v[42:45]
	v_mfma_f32_16x16x32_bf16 v[42:45], v[18:21], v[50:53], 0
	v_mfma_f32_16x16x32_bf16 v[114:117], v[22:25], v[54:57], v[42:45]
	v_mfma_f32_16x16x32_bf16 v[42:45], v[26:29], v[50:53], 0
	v_mfma_f32_16x16x32_bf16 v[50:53], v[30:33], v[54:57], v[42:45]
	v_mfma_f32_16x16x32_bf16 v[42:45], v[18:21], v[58:61], 0
	v_mfma_f32_16x16x32_bf16 v[54:57], v[22:25], v[62:65], v[42:45]
	v_mfma_f32_16x16x32_bf16 v[42:45], v[26:29], v[58:61], 0
	v_mfma_f32_16x16x32_bf16 v[38:41], v[22:25], v[46:49], v[38:41]
	s_setprio 0
	v_mfma_f32_16x16x32_bf16 v[58:61], v[30:33], v[62:65], v[42:45]
	s_barrier
	s_add_i32 s19, s19, s39
	v_lshl_add_u64 v[148:149], s[4:5], 0, v[0:1]
	s_mov_b32 m0, s19
	s_nop 0
	ds_read_b128 v[42:45], v139 offset:16384
	ds_read_b128 v[46:49], v139 offset:17408
	ds_read_b128 v[62:65], v139 offset:18432
	ds_read_b128 v[106:109], v139 offset:19456
	ds_read_b128 v[110:113], v139 offset:20480
	ds_read_b128 v[118:121], v139 offset:21504
	ds_read_b128 v[122:125], v139 offset:22528
	ds_read_b128 v[126:129], v139 offset:23552
	global_load_lds_dwordx4 v[148:149], off
	s_add_i32 m0, s19, 0x2000
	s_add_u32 s26, s4, 0x8000
	v_lshl_add_u64 v[150:151], s[4:5], 0, v[130:131]
	s_addc_u32 s27, s5, 0
	s_add_i32 s19, s48, s39
	global_load_lds_dwordx4 v[150:151], off
	v_lshl_add_u64 v[140:141], s[26:27], 0, v[0:1]
	s_mov_b32 m0, s19
	v_lshl_add_u64 v[252:253], s[22:23], 0, v[134:135]
	global_load_lds_dwordx4 v[140:141], off
	v_lshl_add_u64 v[140:141], s[26:27], 0, v[130:131]
	s_add_i32 m0, s19, 0x2000
	v_lshl_add_u64 v[242:243], s[22:23], 0, v[132:133]
	global_load_lds_dwordx4 v[140:141], off
	s_mov_b32 m0, s40
	s_nop 0
	global_load_lds_dwordx4 v[252:253], off
	s_mov_b32 m0, s41
	s_nop 0
	global_load_lds_dwordx4 v[242:243], off
	s_waitcnt vmcnt(8)
	s_waitcnt lgkmcnt(0)
	s_setprio 1
	s_barrier
	v_mfma_f32_16x16x32_bf16 v[140:143], v[2:5], v[42:45], 0
	v_mfma_f32_16x16x32_bf16 v[156:159], v[2:5], v[62:65], 0
	v_mfma_f32_16x16x32_bf16 v[164:167], v[2:5], v[110:113], 0
	v_mfma_f32_16x16x32_bf16 v[2:5], v[2:5], v[122:125], 0
	v_mfma_f32_16x16x32_bf16 v[140:143], v[6:9], v[46:49], v[140:143]
	v_mfma_f32_16x16x32_bf16 v[156:159], v[6:9], v[106:109], v[156:159]
	v_mfma_f32_16x16x32_bf16 v[164:167], v[6:9], v[118:121], v[164:167]
	v_mfma_f32_16x16x32_bf16 v[2:5], v[6:9], v[126:129], v[2:5]
	v_mfma_f32_16x16x32_bf16 v[6:9], v[10:13], v[122:125], 0
	v_mfma_f32_16x16x32_bf16 v[144:147], v[10:13], v[42:45], 0
	v_mfma_f32_16x16x32_bf16 v[160:163], v[10:13], v[62:65], 0
	v_mfma_f32_16x16x32_bf16 v[168:171], v[10:13], v[110:113], 0
	v_mfma_f32_16x16x32_bf16 v[6:9], v[14:17], v[126:129], v[6:9]
	v_mfma_f32_16x16x32_bf16 v[144:147], v[14:17], v[46:49], v[144:147]
	v_mfma_f32_16x16x32_bf16 v[160:163], v[14:17], v[106:109], v[160:163]
	v_mfma_f32_16x16x32_bf16 v[168:171], v[14:17], v[118:121], v[168:171]
	v_mfma_f32_16x16x32_bf16 v[10:13], v[18:21], v[42:45], 0
	v_mfma_f32_16x16x32_bf16 v[172:175], v[22:25], v[46:49], v[10:13]
	v_mfma_f32_16x16x32_bf16 v[10:13], v[26:29], v[42:45], 0
	v_mfma_f32_16x16x32_bf16 v[176:179], v[30:33], v[46:49], v[10:13]
	v_mfma_f32_16x16x32_bf16 v[10:13], v[18:21], v[62:65], 0
	v_mfma_f32_16x16x32_bf16 v[180:183], v[22:25], v[106:109], v[10:13]
	v_mfma_f32_16x16x32_bf16 v[10:13], v[26:29], v[62:65], 0
	v_mfma_f32_16x16x32_bf16 v[184:187], v[30:33], v[106:109], v[10:13]
	v_mfma_f32_16x16x32_bf16 v[10:13], v[18:21], v[110:113], 0
	v_mfma_f32_16x16x32_bf16 v[188:191], v[22:25], v[118:121], v[10:13]
	v_mfma_f32_16x16x32_bf16 v[10:13], v[26:29], v[110:113], 0
	v_mfma_f32_16x16x32_bf16 v[192:195], v[30:33], v[118:121], v[10:13]
	v_mfma_f32_16x16x32_bf16 v[10:13], v[18:21], v[122:125], 0
	v_mfma_f32_16x16x32_bf16 v[18:21], v[22:25], v[126:129], v[10:13]
	v_mfma_f32_16x16x32_bf16 v[10:13], v[26:29], v[122:125], 0
	s_setprio 0
	v_mfma_f32_16x16x32_bf16 v[22:25], v[30:33], v[126:129], v[10:13]
	s_barrier
	s_add_i32 s19, 0, 0x18000
	s_nop 3
	v_add_u32_e32 v10, s19, v137
	s_add_i32 s36, 0, 0x1c000
	ds_read_b128 v[118:121], v10
	ds_read_b128 v[196:199], v10 offset:1024
	ds_read_b128 v[200:203], v10 offset:2048
	ds_read_b128 v[204:207], v10 offset:3072
	v_add_u32_e32 v10, s36, v137
	ds_read_b128 v[208:211], v10
	ds_read_b128 v[212:215], v10 offset:1024
	ds_read_b128 v[216:219], v10 offset:2048
	ds_read_b128 v[220:223], v10 offset:3072
	s_add_u32 s26, s22, 0x58000
	s_addc_u32 s27, s23, 0
	s_mov_b32 m0, s42
	v_lshl_add_u64 v[10:11], s[26:27], 0, v[134:135]
	ds_read_b128 v[26:29], v139 offset:32768
	ds_read_b128 v[30:33], v139 offset:33792
	ds_read_b128 v[62:65], v139 offset:34816
	ds_read_b128 v[224:227], v139 offset:35840
	ds_read_b128 v[228:231], v139 offset:36864
	ds_read_b128 v[232:235], v139 offset:37888
	ds_read_b128 v[236:239], v139 offset:38912
	ds_read_b128 v[248:251], v139 offset:39936
	global_load_lds_dwordx4 v[10:11], off
	s_mov_b32 m0, s43
	v_lshl_add_u64 v[10:11], s[26:27], 0, v[132:133]
	global_load_lds_dwordx4 v[10:11], off
	s_waitcnt vmcnt(8)
	s_waitcnt lgkmcnt(0)
	s_setprio 1
	s_barrier
	v_mfma_f32_16x16x32_bf16 v[10:13], v[118:121], v[26:29], v[66:69]
	v_mfma_f32_16x16x32_bf16 v[106:109], v[196:199], v[30:33], v[10:13]
	v_mfma_f32_16x16x32_bf16 v[10:13], v[200:203], v[26:29], v[70:73]
	v_mfma_f32_16x16x32_bf16 v[110:113], v[204:207], v[30:33], v[10:13]
	v_mfma_f32_16x16x32_bf16 v[10:13], v[118:121], v[62:65], v[74:77]
	v_mfma_f32_16x16x32_bf16 v[74:77], v[196:199], v[224:227], v[10:13]
	v_mfma_f32_16x16x32_bf16 v[10:13], v[200:203], v[62:65], v[78:81]
	v_mfma_f32_16x16x32_bf16 v[78:81], v[204:207], v[224:227], v[10:13]
	v_mfma_f32_16x16x32_bf16 v[10:13], v[118:121], v[228:231], v[82:85]
	v_mfma_f32_16x16x32_bf16 v[42:45], v[196:199], v[232:235], v[10:13]
	v_mfma_f32_16x16x32_bf16 v[10:13], v[200:203], v[228:231], v[86:89]
	v_mfma_f32_16x16x32_bf16 v[46:49], v[204:207], v[232:235], v[10:13]
	v_mfma_f32_16x16x32_bf16 v[10:13], v[118:121], v[236:239], v[90:93]
	v_mfma_f32_16x16x32_bf16 v[14:17], v[200:203], v[236:239], v[94:97]
	v_mfma_f32_16x16x32_bf16 v[10:13], v[196:199], v[248:251], v[10:13]
	v_mfma_f32_16x16x32_bf16 v[14:17], v[204:207], v[248:251], v[14:17]
	v_mfma_f32_16x16x32_bf16 v[66:69], v[208:211], v[26:29], v[98:101]
	v_mfma_f32_16x16x32_bf16 v[26:29], v[216:219], v[26:29], v[34:37]
	v_mfma_f32_16x16x32_bf16 v[126:129], v[220:223], v[30:33], v[26:29]
	v_mfma_f32_16x16x32_bf16 v[26:29], v[208:211], v[62:65], v[38:41]
	v_mfma_f32_16x16x32_bf16 v[98:101], v[212:215], v[224:227], v[26:29]
	v_mfma_f32_16x16x32_bf16 v[26:29], v[216:219], v[62:65], v[102:105]
	v_mfma_f32_16x16x32_bf16 v[102:105], v[220:223], v[224:227], v[26:29]
	v_mfma_f32_16x16x32_bf16 v[26:29], v[208:211], v[228:231], v[114:117]
	v_mfma_f32_16x16x32_bf16 v[122:125], v[212:215], v[30:33], v[66:69]
	v_mfma_f32_16x16x32_bf16 v[66:69], v[212:215], v[232:235], v[26:29]
	v_mfma_f32_16x16x32_bf16 v[26:29], v[216:219], v[228:231], v[50:53]
	v_mfma_f32_16x16x32_bf16 v[70:73], v[220:223], v[232:235], v[26:29]
	v_mfma_f32_16x16x32_bf16 v[26:29], v[208:211], v[236:239], v[54:57]
	v_mfma_f32_16x16x32_bf16 v[34:37], v[212:215], v[248:251], v[26:29]
	v_mfma_f32_16x16x32_bf16 v[26:29], v[216:219], v[236:239], v[58:61]
	s_setprio 0
	v_mfma_f32_16x16x32_bf16 v[38:41], v[220:223], v[248:251], v[26:29]
	s_barrier
	s_add_i32 s19, s19, s39
	s_nop 3
	v_lshl_add_u64 v[26:27], v[148:149], 0, s[70:71]
	s_mov_b32 m0, s19
	ds_read_b128 v[50:53], v139 offset:49152
	ds_read_b128 v[54:57], v139 offset:50176
	ds_read_b128 v[86:89], v139 offset:51200
	ds_read_b128 v[224:227], v139 offset:52224
	ds_read_b128 v[228:231], v139 offset:53248
	ds_read_b128 v[232:235], v139 offset:54272
	ds_read_b128 v[236:239], v139 offset:55296
	ds_read_b128 v[248:251], v139 offset:56320
	global_load_lds_dwordx4 v[26:27], off
	s_add_i32 m0, s19, 0x2000
	s_add_u32 s4, s4, 0x8080
	v_lshl_add_u64 v[26:27], v[150:151], 0, s[70:71]
	s_addc_u32 s5, s5, 0
	s_add_i32 s19, s36, s39
	global_load_lds_dwordx4 v[26:27], off
	s_mov_b32 m0, s19
	v_lshl_add_u64 v[26:27], s[4:5], 0, v[0:1]
	global_load_lds_dwordx4 v[26:27], off
	s_add_i32 m0, s19, 0x2000
	v_lshl_add_u64 v[26:27], s[4:5], 0, v[130:131]
	global_load_lds_dwordx4 v[26:27], off
	s_mov_b32 m0, s44
	v_lshl_add_u64 v[26:27], v[252:253], 0, s[70:71]
	global_load_lds_dwordx4 v[26:27], off
	s_mov_b32 m0, s45
	v_lshl_add_u64 v[26:27], v[242:243], 0, s[70:71]
	global_load_lds_dwordx4 v[26:27], off
	s_waitcnt vmcnt(8)
	s_waitcnt lgkmcnt(0)
	s_setprio 1
	s_barrier
	v_mfma_f32_16x16x32_bf16 v[26:29], v[118:121], v[50:53], v[140:143]
	v_mfma_f32_16x16x32_bf16 v[90:93], v[196:199], v[54:57], v[26:29]
	v_mfma_f32_16x16x32_bf16 v[26:29], v[200:203], v[50:53], v[144:147]
	v_mfma_f32_16x16x32_bf16 v[94:97], v[204:207], v[54:57], v[26:29]
	v_mfma_f32_16x16x32_bf16 v[26:29], v[118:121], v[86:89], v[156:159]
	v_mfma_f32_16x16x32_bf16 v[58:61], v[196:199], v[224:227], v[26:29]
	v_mfma_f32_16x16x32_bf16 v[26:29], v[200:203], v[86:89], v[160:163]
	v_mfma_f32_16x16x32_bf16 v[62:65], v[204:207], v[224:227], v[26:29]
	v_mfma_f32_16x16x32_bf16 v[26:29], v[118:121], v[228:231], v[164:167]
	v_mfma_f32_16x16x32_bf16 v[30:33], v[200:203], v[228:231], v[168:171]
	v_mfma_f32_16x16x32_bf16 v[2:5], v[118:121], v[236:239], v[2:5]
	v_mfma_f32_16x16x32_bf16 v[6:9], v[200:203], v[236:239], v[6:9]
	v_mfma_f32_16x16x32_bf16 v[26:29], v[196:199], v[232:235], v[26:29]
	v_mfma_f32_16x16x32_bf16 v[30:33], v[204:207], v[232:235], v[30:33]
	v_mfma_f32_16x16x32_bf16 v[2:5], v[196:199], v[248:251], v[2:5]
	v_mfma_f32_16x16x32_bf16 v[6:9], v[204:207], v[248:251], v[6:9]
	v_mfma_f32_16x16x32_bf16 v[82:85], v[208:211], v[50:53], v[172:175]
	v_mfma_f32_16x16x32_bf16 v[50:53], v[216:219], v[50:53], v[176:179]
	v_mfma_f32_16x16x32_bf16 v[118:121], v[220:223], v[54:57], v[50:53]
	v_mfma_f32_16x16x32_bf16 v[50:53], v[208:211], v[86:89], v[180:183]
	v_mfma_f32_16x16x32_bf16 v[114:117], v[212:215], v[54:57], v[82:85]
	v_mfma_f32_16x16x32_bf16 v[82:85], v[212:215], v[224:227], v[50:53]
	v_mfma_f32_16x16x32_bf16 v[50:53], v[216:219], v[86:89], v[184:187]
	v_mfma_f32_16x16x32_bf16 v[86:89], v[220:223], v[224:227], v[50:53]
	v_mfma_f32_16x16x32_bf16 v[50:53], v[208:211], v[228:231], v[188:191]
	v_mfma_f32_16x16x32_bf16 v[54:57], v[216:219], v[228:231], v[192:195]
	v_mfma_f32_16x16x32_bf16 v[18:21], v[208:211], v[236:239], v[18:21]
	v_mfma_f32_16x16x32_bf16 v[22:25], v[216:219], v[236:239], v[22:25]
	v_mfma_f32_16x16x32_bf16 v[50:53], v[212:215], v[232:235], v[50:53]
	v_mfma_f32_16x16x32_bf16 v[54:57], v[220:223], v[232:235], v[54:57]
	v_mfma_f32_16x16x32_bf16 v[18:21], v[212:215], v[248:251], v[18:21]
	s_setprio 0
	v_mfma_f32_16x16x32_bf16 v[22:25], v[220:223], v[248:251], v[22:25]
	s_barrier
	s_andn2_b64 vcc, exec, s[14:15]
	s_cbranch_vccnz .LBB0_395
	s_barrier

.LBB0_701:
	s_add_i32 s75, s26, 2
	s_add_u32 s9, s60, 0xfffc0080
	s_addc_u32 s27, s61, -1
	s_add_i32 s78, 0, 0x10000
	s_cmp_eq_u32 s19, s26
	s_cselect_b32 s73, s23, s27
	s_cselect_b32 s72, s22, s9
	s_cselect_b32 s27, s25, s29
	s_cselect_b32 s26, s24, s28
	s_add_i32 s9, 0, 0x14000
	s_waitcnt vmcnt(0)
	v_add_u32_e32 v142, s78, v177
	v_add_u32_e32 v148, s9, v177
	ds_read_b128 v[130:133], v142
	ds_read_b128 v[134:137], v142 offset:1024
	ds_read_b128 v[138:141], v142 offset:2048
	ds_read_b128 v[142:145], v142 offset:3072
	ds_read_b128 v[164:167], v148
	ds_read_b128 v[168:171], v148 offset:1024
	ds_read_b128 v[172:175], v148 offset:2048
	ds_read_b128 v[180:183], v148 offset:3072
	v_lshl_add_u64 v[148:149], s[60:61], 0, v[160:161]
	s_add_i32 m0, s37, 0xc000
	ds_read_b128 v[184:187], v179
	ds_read_b128 v[188:191], v179 offset:1024
	ds_read_b128 v[192:195], v179 offset:2048
	ds_read_b128 v[196:199], v179 offset:3072
	ds_read_b128 v[200:203], v179 offset:4096
	ds_read_b128 v[204:207], v179 offset:5120
	ds_read_b128 v[208:211], v179 offset:6144
	ds_read_b128 v[212:215], v179 offset:7168
	global_load_lds_dwordx4 v[148:149], off
	s_add_i32 m0, s37, 0xe000
	v_lshl_add_u64 v[148:149], s[60:61], 0, v[162:163]
	global_load_lds_dwordx4 v[148:149], off
	s_waitcnt vmcnt(8)
	s_waitcnt lgkmcnt(0)
	s_setprio 1
	s_barrier
	v_mfma_f32_16x16x32_bf16 v[126:129], v[130:133], v[184:187], v[126:129]
	v_mfma_f32_16x16x32_bf16 v[122:125], v[138:141], v[184:187], v[122:125]
	v_mfma_f32_16x16x32_bf16 v[110:113], v[130:133], v[192:195], v[110:113]
	v_mfma_f32_16x16x32_bf16 v[106:109], v[138:141], v[192:195], v[106:109]
	v_mfma_f32_16x16x32_bf16 v[94:97], v[130:133], v[200:203], v[94:97]
	v_mfma_f32_16x16x32_bf16 v[90:93], v[138:141], v[200:203], v[90:93]
	v_mfma_f32_16x16x32_bf16 v[78:81], v[130:133], v[208:211], v[78:81]
	v_mfma_f32_16x16x32_bf16 v[74:77], v[138:141], v[208:211], v[74:77]
	v_mfma_f32_16x16x32_bf16 v[126:129], v[134:137], v[188:191], v[126:129]
	v_mfma_f32_16x16x32_bf16 v[122:125], v[142:145], v[188:191], v[122:125]
	v_mfma_f32_16x16x32_bf16 v[110:113], v[134:137], v[196:199], v[110:113]
	v_mfma_f32_16x16x32_bf16 v[106:109], v[142:145], v[196:199], v[106:109]
	v_mfma_f32_16x16x32_bf16 v[94:97], v[134:137], v[204:207], v[94:97]
	v_mfma_f32_16x16x32_bf16 v[90:93], v[142:145], v[204:207], v[90:93]
	v_mfma_f32_16x16x32_bf16 v[78:81], v[134:137], v[212:215], v[78:81]
	v_mfma_f32_16x16x32_bf16 v[74:77], v[142:145], v[212:215], v[74:77]
	v_mfma_f32_16x16x32_bf16 v[118:121], v[164:167], v[184:187], v[118:121]
	v_mfma_f32_16x16x32_bf16 v[114:117], v[172:175], v[184:187], v[114:117]
	v_mfma_f32_16x16x32_bf16 v[102:105], v[164:167], v[192:195], v[102:105]
	v_mfma_f32_16x16x32_bf16 v[98:101], v[172:175], v[192:195], v[98:101]
	v_mfma_f32_16x16x32_bf16 v[86:89], v[164:167], v[200:203], v[86:89]
	v_mfma_f32_16x16x32_bf16 v[82:85], v[172:175], v[200:203], v[82:85]
	v_mfma_f32_16x16x32_bf16 v[70:73], v[164:167], v[208:211], v[70:73]
	v_mfma_f32_16x16x32_bf16 v[66:69], v[172:175], v[208:211], v[66:69]
	v_mfma_f32_16x16x32_bf16 v[118:121], v[168:171], v[188:191], v[118:121]
	v_mfma_f32_16x16x32_bf16 v[114:117], v[180:183], v[188:191], v[114:117]
	v_mfma_f32_16x16x32_bf16 v[102:105], v[168:171], v[196:199], v[102:105]
	v_mfma_f32_16x16x32_bf16 v[98:101], v[180:183], v[196:199], v[98:101]
	v_mfma_f32_16x16x32_bf16 v[86:89], v[168:171], v[204:207], v[86:89]
	v_mfma_f32_16x16x32_bf16 v[82:85], v[180:183], v[204:207], v[82:85]
	v_mfma_f32_16x16x32_bf16 v[70:73], v[168:171], v[212:215], v[70:73]
	s_setprio 0
	v_mfma_f32_16x16x32_bf16 v[66:69], v[180:183], v[212:215], v[66:69]
	s_barrier
	s_add_i32 s78, s78, s41
	v_lshl_add_u64 v[148:149], s[26:27], 0, v[0:1]
	s_mov_b32 m0, s78
	ds_read_b128 v[184:187], v179 offset:16384
	ds_read_b128 v[188:191], v179 offset:17408
	ds_read_b128 v[192:195], v179 offset:18432
	ds_read_b128 v[196:199], v179 offset:19456
	ds_read_b128 v[200:203], v179 offset:20480
	ds_read_b128 v[204:207], v179 offset:21504
	ds_read_b128 v[208:211], v179 offset:22528
	ds_read_b128 v[212:215], v179 offset:23552
	global_load_lds_dwordx4 v[148:149], off
	s_add_i32 m0, s78, 0x2000
	s_add_u32 s78, s26, 0x40000
	v_lshl_add_u64 v[150:151], s[26:27], 0, v[158:159]
	s_addc_u32 s79, s27, 0
	s_add_i32 s9, s9, s41
	global_load_lds_dwordx4 v[150:151], off
	v_lshl_add_u64 v[216:217], s[78:79], 0, v[0:1]
	s_mov_b32 m0, s9
	v_lshl_add_u64 v[218:219], s[72:73], 0, v[156:157]
	global_load_lds_dwordx4 v[216:217], off
	s_add_i32 m0, s9, 0x2000
	v_lshl_add_u64 v[216:217], s[78:79], 0, v[158:159]
	global_load_lds_dwordx4 v[216:217], off
	s_mov_b32 m0, s37
	v_lshl_add_u64 v[216:217], s[72:73], 0, v[146:147]
	global_load_lds_dwordx4 v[216:217], off
	s_mov_b32 m0, s39
	s_nop 0
	global_load_lds_dwordx4 v[218:219], off
	s_waitcnt vmcnt(8)
	s_waitcnt lgkmcnt(0)
	s_setprio 1
	s_barrier
	v_mfma_f32_16x16x32_bf16 v[62:65], v[130:133], v[184:187], v[62:65]
	v_mfma_f32_16x16x32_bf16 v[58:61], v[138:141], v[184:187], v[58:61]
	v_mfma_f32_16x16x32_bf16 v[46:49], v[130:133], v[192:195], v[46:49]
	v_mfma_f32_16x16x32_bf16 v[42:45], v[138:141], v[192:195], v[42:45]
	v_mfma_f32_16x16x32_bf16 v[30:33], v[130:133], v[200:203], v[30:33]
	v_mfma_f32_16x16x32_bf16 v[26:29], v[138:141], v[200:203], v[26:29]
	v_mfma_f32_16x16x32_bf16 v[14:17], v[130:133], v[208:211], v[14:17]
	v_mfma_f32_16x16x32_bf16 v[10:13], v[138:141], v[208:211], v[10:13]
	v_mfma_f32_16x16x32_bf16 v[62:65], v[134:137], v[188:191], v[62:65]
	v_mfma_f32_16x16x32_bf16 v[58:61], v[142:145], v[188:191], v[58:61]
	v_mfma_f32_16x16x32_bf16 v[46:49], v[134:137], v[196:199], v[46:49]
	v_mfma_f32_16x16x32_bf16 v[42:45], v[142:145], v[196:199], v[42:45]
	v_mfma_f32_16x16x32_bf16 v[30:33], v[134:137], v[204:207], v[30:33]
	v_mfma_f32_16x16x32_bf16 v[26:29], v[142:145], v[204:207], v[26:29]
	v_mfma_f32_16x16x32_bf16 v[14:17], v[134:137], v[212:215], v[14:17]
	v_mfma_f32_16x16x32_bf16 v[10:13], v[142:145], v[212:215], v[10:13]
	v_mfma_f32_16x16x32_bf16 v[54:57], v[164:167], v[184:187], v[54:57]
	v_mfma_f32_16x16x32_bf16 v[50:53], v[172:175], v[184:187], v[50:53]
	v_mfma_f32_16x16x32_bf16 v[38:41], v[164:167], v[192:195], v[38:41]
	v_mfma_f32_16x16x32_bf16 v[34:37], v[172:175], v[192:195], v[34:37]
	v_mfma_f32_16x16x32_bf16 v[22:25], v[164:167], v[200:203], v[22:25]
	v_mfma_f32_16x16x32_bf16 v[18:21], v[172:175], v[200:203], v[18:21]
	v_mfma_f32_16x16x32_bf16 v[6:9], v[164:167], v[208:211], v[6:9]
	v_mfma_f32_16x16x32_bf16 v[2:5], v[172:175], v[208:211], v[2:5]
	v_mfma_f32_16x16x32_bf16 v[54:57], v[168:171], v[188:191], v[54:57]
	v_mfma_f32_16x16x32_bf16 v[50:53], v[180:183], v[188:191], v[50:53]
	v_mfma_f32_16x16x32_bf16 v[38:41], v[168:171], v[196:199], v[38:41]
	v_mfma_f32_16x16x32_bf16 v[34:37], v[180:183], v[196:199], v[34:37]
	v_mfma_f32_16x16x32_bf16 v[22:25], v[168:171], v[204:207], v[22:25]
	v_mfma_f32_16x16x32_bf16 v[18:21], v[180:183], v[204:207], v[18:21]
	v_mfma_f32_16x16x32_bf16 v[6:9], v[168:171], v[212:215], v[6:9]
	s_setprio 0
	v_mfma_f32_16x16x32_bf16 v[2:5], v[180:183], v[212:215], v[2:5]
	s_barrier
	s_add_i32 s9, 0, 0x18000
	s_add_i32 s78, 0, 0x1c000
	v_add_u32_e32 v142, s9, v177
	v_add_u32_e32 v180, s78, v177
	ds_read_b128 v[130:133], v142
	ds_read_b128 v[134:137], v142 offset:1024
	ds_read_b128 v[138:141], v142 offset:2048
	ds_read_b128 v[142:145], v142 offset:3072
	ds_read_b128 v[164:167], v180
	ds_read_b128 v[168:171], v180 offset:1024
	ds_read_b128 v[172:175], v180 offset:2048
	ds_read_b128 v[180:183], v180 offset:3072
	s_add_u32 s72, s72, 0x40000
	s_addc_u32 s73, s73, 0
	s_mov_b32 m0, s44
	v_lshl_add_u64 v[220:221], s[72:73], 0, v[146:147]
	ds_read_b128 v[184:187], v179 offset:32768
	ds_read_b128 v[188:191], v179 offset:33792
	ds_read_b128 v[192:195], v179 offset:34816
	ds_read_b128 v[196:199], v179 offset:35840
	ds_read_b128 v[200:203], v179 offset:36864
	ds_read_b128 v[204:207], v179 offset:37888
	ds_read_b128 v[208:211], v179 offset:38912
	ds_read_b128 v[212:215], v179 offset:39936
	global_load_lds_dwordx4 v[220:221], off
	s_mov_b32 m0, s45
	v_lshl_add_u64 v[220:221], s[72:73], 0, v[156:157]
	global_load_lds_dwordx4 v[220:221], off
	s_waitcnt vmcnt(8)
	s_waitcnt lgkmcnt(0)
	s_setprio 1
	s_barrier
	v_mfma_f32_16x16x32_bf16 v[126:129], v[130:133], v[184:187], v[126:129]
	v_mfma_f32_16x16x32_bf16 v[122:125], v[138:141], v[184:187], v[122:125]
	v_mfma_f32_16x16x32_bf16 v[110:113], v[130:133], v[192:195], v[110:113]
	v_mfma_f32_16x16x32_bf16 v[106:109], v[138:141], v[192:195], v[106:109]
	v_mfma_f32_16x16x32_bf16 v[94:97], v[130:133], v[200:203], v[94:97]
	v_mfma_f32_16x16x32_bf16 v[90:93], v[138:141], v[200:203], v[90:93]
	v_mfma_f32_16x16x32_bf16 v[78:81], v[130:133], v[208:211], v[78:81]
	v_mfma_f32_16x16x32_bf16 v[74:77], v[138:141], v[208:211], v[74:77]
	v_mfma_f32_16x16x32_bf16 v[126:129], v[134:137], v[188:191], v[126:129]
	v_mfma_f32_16x16x32_bf16 v[122:125], v[142:145], v[188:191], v[122:125]
	v_mfma_f32_16x16x32_bf16 v[110:113], v[134:137], v[196:199], v[110:113]
	v_mfma_f32_16x16x32_bf16 v[106:109], v[142:145], v[196:199], v[106:109]
	v_mfma_f32_16x16x32_bf16 v[94:97], v[134:137], v[204:207], v[94:97]
	v_mfma_f32_16x16x32_bf16 v[90:93], v[142:145], v[204:207], v[90:93]
	v_mfma_f32_16x16x32_bf16 v[78:81], v[134:137], v[212:215], v[78:81]
	v_mfma_f32_16x16x32_bf16 v[74:77], v[142:145], v[212:215], v[74:77]
	v_mfma_f32_16x16x32_bf16 v[118:121], v[164:167], v[184:187], v[118:121]
	v_mfma_f32_16x16x32_bf16 v[114:117], v[172:175], v[184:187], v[114:117]
	v_mfma_f32_16x16x32_bf16 v[102:105], v[164:167], v[192:195], v[102:105]
	v_mfma_f32_16x16x32_bf16 v[98:101], v[172:175], v[192:195], v[98:101]
	v_mfma_f32_16x16x32_bf16 v[86:89], v[164:167], v[200:203], v[86:89]
	v_mfma_f32_16x16x32_bf16 v[82:85], v[172:175], v[200:203], v[82:85]
	v_mfma_f32_16x16x32_bf16 v[70:73], v[164:167], v[208:211], v[70:73]
	v_mfma_f32_16x16x32_bf16 v[66:69], v[172:175], v[208:211], v[66:69]
	v_mfma_f32_16x16x32_bf16 v[118:121], v[168:171], v[188:191], v[118:121]
	v_mfma_f32_16x16x32_bf16 v[114:117], v[180:183], v[188:191], v[114:117]
	v_mfma_f32_16x16x32_bf16 v[102:105], v[168:171], v[196:199], v[102:105]
	v_mfma_f32_16x16x32_bf16 v[98:101], v[180:183], v[196:199], v[98:101]
	v_mfma_f32_16x16x32_bf16 v[86:89], v[168:171], v[204:207], v[86:89]
	v_mfma_f32_16x16x32_bf16 v[82:85], v[180:183], v[204:207], v[82:85]
	v_mfma_f32_16x16x32_bf16 v[70:73], v[168:171], v[212:215], v[70:73]
	s_setprio 0
	v_mfma_f32_16x16x32_bf16 v[66:69], v[180:183], v[212:215], v[66:69]
	s_barrier
	s_add_i32 s9, s9, s41
	v_lshl_add_u64 v[148:149], v[148:149], 0, s[70:71]
	s_mov_b32 m0, s9
	ds_read_b128 v[184:187], v179 offset:49152
	ds_read_b128 v[188:191], v179 offset:50176
	ds_read_b128 v[192:195], v179 offset:51200
	ds_read_b128 v[196:199], v179 offset:52224
	ds_read_b128 v[200:203], v179 offset:53248
	ds_read_b128 v[204:207], v179 offset:54272
	ds_read_b128 v[208:211], v179 offset:55296
	ds_read_b128 v[212:215], v179 offset:56320
	global_load_lds_dwordx4 v[148:149], off
	s_add_i32 m0, s9, 0x2000
	s_add_u32 s26, s26, 0x40080
	v_lshl_add_u64 v[148:149], v[150:151], 0, s[70:71]
	s_addc_u32 s27, s27, 0
	s_add_i32 s9, s78, s41
	global_load_lds_dwordx4 v[148:149], off
	s_mov_b32 m0, s9
	v_lshl_add_u64 v[148:149], s[26:27], 0, v[0:1]
	global_load_lds_dwordx4 v[148:149], off
	s_add_i32 m0, s9, 0x2000
	v_lshl_add_u64 v[148:149], s[26:27], 0, v[158:159]
	global_load_lds_dwordx4 v[148:149], off
	s_mov_b32 m0, s50
	v_lshl_add_u64 v[148:149], v[216:217], 0, s[70:71]
	global_load_lds_dwordx4 v[148:149], off
	s_mov_b32 m0, s51
	v_lshl_add_u64 v[148:149], v[218:219], 0, s[70:71]
	global_load_lds_dwordx4 v[148:149], off
	s_waitcnt vmcnt(8)
	s_waitcnt lgkmcnt(0)
	s_setprio 1
	s_barrier
	v_mfma_f32_16x16x32_bf16 v[62:65], v[130:133], v[184:187], v[62:65]
	v_mfma_f32_16x16x32_bf16 v[58:61], v[138:141], v[184:187], v[58:61]
	v_mfma_f32_16x16x32_bf16 v[46:49], v[130:133], v[192:195], v[46:49]
	v_mfma_f32_16x16x32_bf16 v[42:45], v[138:141], v[192:195], v[42:45]
	v_mfma_f32_16x16x32_bf16 v[30:33], v[130:133], v[200:203], v[30:33]
	v_mfma_f32_16x16x32_bf16 v[26:29], v[138:141], v[200:203], v[26:29]
	v_mfma_f32_16x16x32_bf16 v[14:17], v[130:133], v[208:211], v[14:17]
	v_mfma_f32_16x16x32_bf16 v[10:13], v[138:141], v[208:211], v[10:13]
	v_mfma_f32_16x16x32_bf16 v[62:65], v[134:137], v[188:191], v[62:65]
	v_mfma_f32_16x16x32_bf16 v[58:61], v[142:145], v[188:191], v[58:61]
	v_mfma_f32_16x16x32_bf16 v[46:49], v[134:137], v[196:199], v[46:49]
	v_mfma_f32_16x16x32_bf16 v[42:45], v[142:145], v[196:199], v[42:45]
	v_mfma_f32_16x16x32_bf16 v[30:33], v[134:137], v[204:207], v[30:33]
	v_mfma_f32_16x16x32_bf16 v[26:29], v[142:145], v[204:207], v[26:29]
	v_mfma_f32_16x16x32_bf16 v[14:17], v[134:137], v[212:215], v[14:17]
	v_mfma_f32_16x16x32_bf16 v[10:13], v[142:145], v[212:215], v[10:13]
	v_mfma_f32_16x16x32_bf16 v[54:57], v[164:167], v[184:187], v[54:57]
	v_mfma_f32_16x16x32_bf16 v[50:53], v[172:175], v[184:187], v[50:53]
	v_mfma_f32_16x16x32_bf16 v[38:41], v[164:167], v[192:195], v[38:41]
	v_mfma_f32_16x16x32_bf16 v[34:37], v[172:175], v[192:195], v[34:37]
	v_mfma_f32_16x16x32_bf16 v[22:25], v[164:167], v[200:203], v[22:25]
	v_mfma_f32_16x16x32_bf16 v[18:21], v[172:175], v[200:203], v[18:21]
	v_mfma_f32_16x16x32_bf16 v[6:9], v[164:167], v[208:211], v[6:9]
	v_mfma_f32_16x16x32_bf16 v[2:5], v[172:175], v[208:211], v[2:5]
	v_mfma_f32_16x16x32_bf16 v[54:57], v[168:171], v[188:191], v[54:57]
	v_mfma_f32_16x16x32_bf16 v[50:53], v[180:183], v[188:191], v[50:53]
	v_mfma_f32_16x16x32_bf16 v[38:41], v[168:171], v[196:199], v[38:41]
	v_mfma_f32_16x16x32_bf16 v[34:37], v[180:183], v[196:199], v[34:37]
	v_mfma_f32_16x16x32_bf16 v[22:25], v[168:171], v[204:207], v[22:25]
	v_mfma_f32_16x16x32_bf16 v[18:21], v[180:183], v[204:207], v[18:21]
	v_mfma_f32_16x16x32_bf16 v[6:9], v[168:171], v[212:215], v[6:9]
	s_setprio 0
	v_mfma_f32_16x16x32_bf16 v[2:5], v[180:183], v[212:215], v[2:5]
	s_barrier
	s_add_u32 s60, s60, 0x100
	s_addc_u32 s61, s61, 0
	s_add_u32 s28, s28, 0x100
	s_addc_u32 s29, s29, 0
	s_cmp_ge_u32 s75, s17
	s_mov_b32 s26, s75
	s_cbranch_scc0 .LBB0_701
	s_and_b64 vcc, exec, s[14:15]
	s_cbranch_vccz .LBB0_704

.LBB0_846:
	s_add_u32 s9, s96, 0xfffc0080
	s_addc_u32 s38, s97, -1
	s_add_i32 s78, 0, 0x10000
	s_cmp_eq_u32 s75, 12
	s_cselect_b32 vcc_hi, s25, s38
	s_cselect_b32 vcc_lo, s28, s9
	v_add_u32_e32 v148, s78, v145
	s_cselect_b32 s39, s23, s61
	s_cselect_b32 s38, s29, s53
	s_add_i32 s9, 0, 0x14000
	ds_read_b128 v[140:143], v148
	ds_read_b128 v[156:159], v148 offset:1024
	ds_read_b128 v[160:163], v148 offset:2048
	ds_read_b128 v[164:167], v148 offset:3072
	v_add_u32_e32 v148, s9, v145
	ds_read_b128 v[168:171], v148
	ds_read_b128 v[172:175], v148 offset:1024
	ds_read_b128 v[176:179], v148 offset:2048
	ds_read_b128 v[180:183], v148 offset:3072
	v_lshl_add_u64 v[148:149], s[96:97], 0, v[136:137]
	s_add_i32 m0, s46, 0xc000
	ds_read_b128 v[184:187], v147
	ds_read_b128 v[188:191], v147 offset:1024
	ds_read_b128 v[192:195], v147 offset:2048
	ds_read_b128 v[196:199], v147 offset:3072
	ds_read_b128 v[200:203], v147 offset:4096
	ds_read_b128 v[204:207], v147 offset:5120
	ds_read_b128 v[208:211], v147 offset:6144
	ds_read_b128 v[212:215], v147 offset:7168
	global_load_lds_dwordx4 v[148:149], off
	s_add_i32 m0, s46, 0xe000
	v_lshl_add_u64 v[148:149], s[96:97], 0, v[138:139]
	global_load_lds_dwordx4 v[148:149], off
	s_waitcnt vmcnt(8)
	s_waitcnt lgkmcnt(0)
	s_setprio 1
	s_barrier
	v_mfma_f32_16x16x32_bf16 v[126:129], v[140:143], v[184:187], v[126:129]
	v_mfma_f32_16x16x32_bf16 v[118:121], v[160:163], v[184:187], v[118:121]
	v_mfma_f32_16x16x32_bf16 v[110:113], v[140:143], v[192:195], v[110:113]
	v_mfma_f32_16x16x32_bf16 v[102:105], v[160:163], v[192:195], v[102:105]
	v_mfma_f32_16x16x32_bf16 v[94:97], v[140:143], v[200:203], v[94:97]
	v_mfma_f32_16x16x32_bf16 v[86:89], v[160:163], v[200:203], v[86:89]
	v_mfma_f32_16x16x32_bf16 v[78:81], v[140:143], v[208:211], v[78:81]
	v_mfma_f32_16x16x32_bf16 v[70:73], v[160:163], v[208:211], v[70:73]
	v_mfma_f32_16x16x32_bf16 v[126:129], v[156:159], v[188:191], v[126:129]
	v_mfma_f32_16x16x32_bf16 v[118:121], v[164:167], v[188:191], v[118:121]
	v_mfma_f32_16x16x32_bf16 v[110:113], v[156:159], v[196:199], v[110:113]
	v_mfma_f32_16x16x32_bf16 v[102:105], v[164:167], v[196:199], v[102:105]
	v_mfma_f32_16x16x32_bf16 v[94:97], v[156:159], v[204:207], v[94:97]
	v_mfma_f32_16x16x32_bf16 v[86:89], v[164:167], v[204:207], v[86:89]
	v_mfma_f32_16x16x32_bf16 v[78:81], v[156:159], v[212:215], v[78:81]
	v_mfma_f32_16x16x32_bf16 v[70:73], v[164:167], v[212:215], v[70:73]
	v_mfma_f32_16x16x32_bf16 v[122:125], v[168:171], v[184:187], v[122:125]
	v_mfma_f32_16x16x32_bf16 v[114:117], v[176:179], v[184:187], v[114:117]
	v_mfma_f32_16x16x32_bf16 v[106:109], v[168:171], v[192:195], v[106:109]
	v_mfma_f32_16x16x32_bf16 v[98:101], v[176:179], v[192:195], v[98:101]
	v_mfma_f32_16x16x32_bf16 v[90:93], v[168:171], v[200:203], v[90:93]
	v_mfma_f32_16x16x32_bf16 v[82:85], v[176:179], v[200:203], v[82:85]
	v_mfma_f32_16x16x32_bf16 v[74:77], v[168:171], v[208:211], v[74:77]
	v_mfma_f32_16x16x32_bf16 v[66:69], v[176:179], v[208:211], v[66:69]
	v_mfma_f32_16x16x32_bf16 v[122:125], v[172:175], v[188:191], v[122:125]
	v_mfma_f32_16x16x32_bf16 v[114:117], v[180:183], v[188:191], v[114:117]
	v_mfma_f32_16x16x32_bf16 v[106:109], v[172:175], v[196:199], v[106:109]
	v_mfma_f32_16x16x32_bf16 v[98:101], v[180:183], v[196:199], v[98:101]
	v_mfma_f32_16x16x32_bf16 v[90:93], v[172:175], v[204:207], v[90:93]
	v_mfma_f32_16x16x32_bf16 v[82:85], v[180:183], v[204:207], v[82:85]
	v_mfma_f32_16x16x32_bf16 v[74:77], v[172:175], v[212:215], v[74:77]
	s_setprio 0
	v_mfma_f32_16x16x32_bf16 v[66:69], v[180:183], v[212:215], v[66:69]
	s_barrier
	s_add_i32 s78, s78, s45
	v_lshl_add_u64 v[148:149], s[38:39], 0, v[0:1]
	s_mov_b32 m0, s78
	ds_read_b128 v[184:187], v147 offset:16384
	ds_read_b128 v[188:191], v147 offset:17408
	ds_read_b128 v[192:195], v147 offset:18432
	ds_read_b128 v[196:199], v147 offset:19456
	ds_read_b128 v[200:203], v147 offset:20480
	ds_read_b128 v[204:207], v147 offset:21504
	ds_read_b128 v[208:211], v147 offset:22528
	ds_read_b128 v[212:215], v147 offset:23552
	global_load_lds_dwordx4 v[148:149], off
	s_add_i32 m0, s78, 0x2000
	s_add_u32 s78, s38, 0x40000
	v_lshl_add_u64 v[150:151], s[38:39], 0, v[134:135]
	s_addc_u32 s79, s39, 0
	s_add_i32 s9, s9, s45
	global_load_lds_dwordx4 v[150:151], off
	v_lshl_add_u64 v[216:217], s[78:79], 0, v[0:1]
	s_mov_b32 m0, s9
	v_lshl_add_u64 v[218:219], vcc, 0, v[132:133]
	global_load_lds_dwordx4 v[216:217], off
	s_add_i32 m0, s9, 0x2000
	v_lshl_add_u64 v[216:217], s[78:79], 0, v[134:135]
	global_load_lds_dwordx4 v[216:217], off
	s_mov_b32 m0, s46
	v_lshl_add_u64 v[216:217], vcc, 0, v[130:131]
	global_load_lds_dwordx4 v[216:217], off
	s_mov_b32 m0, s47
	s_nop 0
	global_load_lds_dwordx4 v[218:219], off
	s_waitcnt vmcnt(8)
	s_waitcnt lgkmcnt(0)
	s_setprio 1
	s_barrier
	v_mfma_f32_16x16x32_bf16 v[62:65], v[140:143], v[184:187], v[62:65]
	v_mfma_f32_16x16x32_bf16 v[54:57], v[160:163], v[184:187], v[54:57]
	v_mfma_f32_16x16x32_bf16 v[46:49], v[140:143], v[192:195], v[46:49]
	v_mfma_f32_16x16x32_bf16 v[38:41], v[160:163], v[192:195], v[38:41]
	v_mfma_f32_16x16x32_bf16 v[30:33], v[140:143], v[200:203], v[30:33]
	v_mfma_f32_16x16x32_bf16 v[22:25], v[160:163], v[200:203], v[22:25]
	v_mfma_f32_16x16x32_bf16 v[14:17], v[140:143], v[208:211], v[14:17]
	v_mfma_f32_16x16x32_bf16 v[6:9], v[160:163], v[208:211], v[6:9]
	v_mfma_f32_16x16x32_bf16 v[62:65], v[156:159], v[188:191], v[62:65]
	v_mfma_f32_16x16x32_bf16 v[54:57], v[164:167], v[188:191], v[54:57]
	v_mfma_f32_16x16x32_bf16 v[46:49], v[156:159], v[196:199], v[46:49]
	v_mfma_f32_16x16x32_bf16 v[38:41], v[164:167], v[196:199], v[38:41]
	v_mfma_f32_16x16x32_bf16 v[30:33], v[156:159], v[204:207], v[30:33]
	v_mfma_f32_16x16x32_bf16 v[22:25], v[164:167], v[204:207], v[22:25]
	v_mfma_f32_16x16x32_bf16 v[14:17], v[156:159], v[212:215], v[14:17]
	v_mfma_f32_16x16x32_bf16 v[6:9], v[164:167], v[212:215], v[6:9]
	v_mfma_f32_16x16x32_bf16 v[58:61], v[168:171], v[184:187], v[58:61]
	v_mfma_f32_16x16x32_bf16 v[50:53], v[176:179], v[184:187], v[50:53]
	v_mfma_f32_16x16x32_bf16 v[42:45], v[168:171], v[192:195], v[42:45]
	v_mfma_f32_16x16x32_bf16 v[34:37], v[176:179], v[192:195], v[34:37]
	v_mfma_f32_16x16x32_bf16 v[26:29], v[168:171], v[200:203], v[26:29]
	v_mfma_f32_16x16x32_bf16 v[18:21], v[176:179], v[200:203], v[18:21]
	v_mfma_f32_16x16x32_bf16 v[10:13], v[168:171], v[208:211], v[10:13]
	v_mfma_f32_16x16x32_bf16 v[2:5], v[176:179], v[208:211], v[2:5]
	v_mfma_f32_16x16x32_bf16 v[58:61], v[172:175], v[188:191], v[58:61]
	v_mfma_f32_16x16x32_bf16 v[50:53], v[180:183], v[188:191], v[50:53]
	v_mfma_f32_16x16x32_bf16 v[42:45], v[172:175], v[196:199], v[42:45]
	v_mfma_f32_16x16x32_bf16 v[34:37], v[180:183], v[196:199], v[34:37]
	v_mfma_f32_16x16x32_bf16 v[26:29], v[172:175], v[204:207], v[26:29]
	v_mfma_f32_16x16x32_bf16 v[18:21], v[180:183], v[204:207], v[18:21]
	v_mfma_f32_16x16x32_bf16 v[10:13], v[172:175], v[212:215], v[10:13]
	s_setprio 0
	v_mfma_f32_16x16x32_bf16 v[2:5], v[180:183], v[212:215], v[2:5]
	s_barrier
	s_add_i32 s9, 0, 0x18000
	s_add_i32 s83, 0, 0x1c000
	v_add_u32_e32 v164, s9, v145
	v_add_u32_e32 v180, s83, v145
	ds_read_b128 v[140:143], v164
	ds_read_b128 v[156:159], v164 offset:1024
	ds_read_b128 v[160:163], v164 offset:2048
	ds_read_b128 v[164:167], v164 offset:3072
	ds_read_b128 v[168:171], v180
	ds_read_b128 v[172:175], v180 offset:1024
	ds_read_b128 v[176:179], v180 offset:2048
	ds_read_b128 v[180:183], v180 offset:3072
	s_add_u32 s78, vcc_lo, 0x40000
	s_addc_u32 s79, vcc_hi, 0
	s_mov_b32 m0, s48
	v_lshl_add_u64 v[220:221], s[78:79], 0, v[130:131]
	ds_read_b128 v[184:187], v147 offset:32768
	ds_read_b128 v[188:191], v147 offset:33792
	ds_read_b128 v[192:195], v147 offset:34816
	ds_read_b128 v[196:199], v147 offset:35840
	ds_read_b128 v[200:203], v147 offset:36864
	ds_read_b128 v[204:207], v147 offset:37888
	ds_read_b128 v[208:211], v147 offset:38912
	ds_read_b128 v[212:215], v147 offset:39936
	global_load_lds_dwordx4 v[220:221], off
	s_mov_b32 m0, s49
	v_lshl_add_u64 v[220:221], s[78:79], 0, v[132:133]
	global_load_lds_dwordx4 v[220:221], off
	s_waitcnt vmcnt(8)
	s_waitcnt lgkmcnt(0)
	s_setprio 1
	s_barrier
	v_mfma_f32_16x16x32_bf16 v[126:129], v[140:143], v[184:187], v[126:129]
	v_mfma_f32_16x16x32_bf16 v[118:121], v[160:163], v[184:187], v[118:121]
	v_mfma_f32_16x16x32_bf16 v[110:113], v[140:143], v[192:195], v[110:113]
	v_mfma_f32_16x16x32_bf16 v[102:105], v[160:163], v[192:195], v[102:105]
	v_mfma_f32_16x16x32_bf16 v[94:97], v[140:143], v[200:203], v[94:97]
	v_mfma_f32_16x16x32_bf16 v[86:89], v[160:163], v[200:203], v[86:89]
	v_mfma_f32_16x16x32_bf16 v[78:81], v[140:143], v[208:211], v[78:81]
	v_mfma_f32_16x16x32_bf16 v[70:73], v[160:163], v[208:211], v[70:73]
	v_mfma_f32_16x16x32_bf16 v[126:129], v[156:159], v[188:191], v[126:129]
	v_mfma_f32_16x16x32_bf16 v[118:121], v[164:167], v[188:191], v[118:121]
	v_mfma_f32_16x16x32_bf16 v[110:113], v[156:159], v[196:199], v[110:113]
	v_mfma_f32_16x16x32_bf16 v[102:105], v[164:167], v[196:199], v[102:105]
	v_mfma_f32_16x16x32_bf16 v[94:97], v[156:159], v[204:207], v[94:97]
	v_mfma_f32_16x16x32_bf16 v[86:89], v[164:167], v[204:207], v[86:89]
	v_mfma_f32_16x16x32_bf16 v[78:81], v[156:159], v[212:215], v[78:81]
	v_mfma_f32_16x16x32_bf16 v[70:73], v[164:167], v[212:215], v[70:73]
	v_mfma_f32_16x16x32_bf16 v[122:125], v[168:171], v[184:187], v[122:125]
	v_mfma_f32_16x16x32_bf16 v[114:117], v[176:179], v[184:187], v[114:117]
	v_mfma_f32_16x16x32_bf16 v[106:109], v[168:171], v[192:195], v[106:109]
	v_mfma_f32_16x16x32_bf16 v[98:101], v[176:179], v[192:195], v[98:101]
	v_mfma_f32_16x16x32_bf16 v[90:93], v[168:171], v[200:203], v[90:93]
	v_mfma_f32_16x16x32_bf16 v[82:85], v[176:179], v[200:203], v[82:85]
	v_mfma_f32_16x16x32_bf16 v[74:77], v[168:171], v[208:211], v[74:77]
	v_mfma_f32_16x16x32_bf16 v[66:69], v[176:179], v[208:211], v[66:69]
	v_mfma_f32_16x16x32_bf16 v[122:125], v[172:175], v[188:191], v[122:125]
	v_mfma_f32_16x16x32_bf16 v[114:117], v[180:183], v[188:191], v[114:117]
	v_mfma_f32_16x16x32_bf16 v[106:109], v[172:175], v[196:199], v[106:109]
	v_mfma_f32_16x16x32_bf16 v[98:101], v[180:183], v[196:199], v[98:101]
	v_mfma_f32_16x16x32_bf16 v[90:93], v[172:175], v[204:207], v[90:93]
	v_mfma_f32_16x16x32_bf16 v[82:85], v[180:183], v[204:207], v[82:85]
	v_mfma_f32_16x16x32_bf16 v[74:77], v[172:175], v[212:215], v[74:77]
	s_setprio 0
	v_mfma_f32_16x16x32_bf16 v[66:69], v[180:183], v[212:215], v[66:69]
	s_barrier
	s_add_i32 s9, s9, s45
	v_lshl_add_u64 v[148:149], v[148:149], 0, s[70:71]
	s_mov_b32 m0, s9
	ds_read_b128 v[184:187], v147 offset:49152
	ds_read_b128 v[188:191], v147 offset:50176
	ds_read_b128 v[192:195], v147 offset:51200
	ds_read_b128 v[196:199], v147 offset:52224
	ds_read_b128 v[200:203], v147 offset:53248
	ds_read_b128 v[204:207], v147 offset:54272
	ds_read_b128 v[208:211], v147 offset:55296
	ds_read_b128 v[212:215], v147 offset:56320
	global_load_lds_dwordx4 v[148:149], off
	s_add_i32 m0, s9, 0x2000
	s_add_u32 s38, s38, 0x40080
	v_lshl_add_u64 v[148:149], v[150:151], 0, s[70:71]
	s_addc_u32 s39, s39, 0
	s_add_i32 s9, s83, s45
	global_load_lds_dwordx4 v[148:149], off
	s_mov_b32 m0, s9
	v_lshl_add_u64 v[148:149], s[38:39], 0, v[0:1]
	global_load_lds_dwordx4 v[148:149], off
	s_add_i32 m0, s9, 0x2000
	v_lshl_add_u64 v[148:149], s[38:39], 0, v[134:135]
	global_load_lds_dwordx4 v[148:149], off
	s_mov_b32 m0, s50
	v_lshl_add_u64 v[148:149], v[216:217], 0, s[70:71]
	global_load_lds_dwordx4 v[148:149], off
	s_mov_b32 m0, s51
	v_lshl_add_u64 v[148:149], v[218:219], 0, s[70:71]
	global_load_lds_dwordx4 v[148:149], off
	s_waitcnt vmcnt(8)
	s_waitcnt lgkmcnt(0)
	s_setprio 1
	s_barrier
	v_mfma_f32_16x16x32_bf16 v[62:65], v[140:143], v[184:187], v[62:65]
	v_mfma_f32_16x16x32_bf16 v[54:57], v[160:163], v[184:187], v[54:57]
	v_mfma_f32_16x16x32_bf16 v[46:49], v[140:143], v[192:195], v[46:49]
	v_mfma_f32_16x16x32_bf16 v[38:41], v[160:163], v[192:195], v[38:41]
	v_mfma_f32_16x16x32_bf16 v[30:33], v[140:143], v[200:203], v[30:33]
	v_mfma_f32_16x16x32_bf16 v[22:25], v[160:163], v[200:203], v[22:25]
	v_mfma_f32_16x16x32_bf16 v[14:17], v[140:143], v[208:211], v[14:17]
	v_mfma_f32_16x16x32_bf16 v[6:9], v[160:163], v[208:211], v[6:9]
	v_mfma_f32_16x16x32_bf16 v[62:65], v[156:159], v[188:191], v[62:65]
	v_mfma_f32_16x16x32_bf16 v[54:57], v[164:167], v[188:191], v[54:57]
	v_mfma_f32_16x16x32_bf16 v[46:49], v[156:159], v[196:199], v[46:49]
	v_mfma_f32_16x16x32_bf16 v[38:41], v[164:167], v[196:199], v[38:41]
	v_mfma_f32_16x16x32_bf16 v[30:33], v[156:159], v[204:207], v[30:33]
	v_mfma_f32_16x16x32_bf16 v[22:25], v[164:167], v[204:207], v[22:25]
	v_mfma_f32_16x16x32_bf16 v[14:17], v[156:159], v[212:215], v[14:17]
	v_mfma_f32_16x16x32_bf16 v[6:9], v[164:167], v[212:215], v[6:9]
	v_mfma_f32_16x16x32_bf16 v[58:61], v[168:171], v[184:187], v[58:61]
	v_mfma_f32_16x16x32_bf16 v[50:53], v[176:179], v[184:187], v[50:53]
	v_mfma_f32_16x16x32_bf16 v[42:45], v[168:171], v[192:195], v[42:45]
	v_mfma_f32_16x16x32_bf16 v[34:37], v[176:179], v[192:195], v[34:37]
	v_mfma_f32_16x16x32_bf16 v[26:29], v[168:171], v[200:203], v[26:29]
	v_mfma_f32_16x16x32_bf16 v[18:21], v[176:179], v[200:203], v[18:21]
	v_mfma_f32_16x16x32_bf16 v[10:13], v[168:171], v[208:211], v[10:13]
	v_mfma_f32_16x16x32_bf16 v[2:5], v[176:179], v[208:211], v[2:5]
	v_mfma_f32_16x16x32_bf16 v[58:61], v[172:175], v[188:191], v[58:61]
	v_mfma_f32_16x16x32_bf16 v[50:53], v[180:183], v[188:191], v[50:53]
	v_mfma_f32_16x16x32_bf16 v[42:45], v[172:175], v[196:199], v[42:45]
	v_mfma_f32_16x16x32_bf16 v[34:37], v[180:183], v[196:199], v[34:37]
	v_mfma_f32_16x16x32_bf16 v[26:29], v[172:175], v[204:207], v[26:29]
	v_mfma_f32_16x16x32_bf16 v[18:21], v[180:183], v[204:207], v[18:21]
	v_mfma_f32_16x16x32_bf16 v[10:13], v[172:175], v[212:215], v[10:13]
	s_setprio 0
	v_mfma_f32_16x16x32_bf16 v[2:5], v[180:183], v[212:215], v[2:5]
	s_barrier
	s_add_i32 s75, s75, 2
	s_add_u32 s96, s96, 0x100
	s_addc_u32 s97, s97, 0
	s_add_u32 s53, s53, 0x100
	s_addc_u32 s61, s61, 0
	s_cmp_gt_u32 s75, 13
	s_cbranch_scc0 .LBB0_846
	s_and_b64 vcc, exec, s[14:15]
	s_cbranch_vccz .LBB0_849
	s_barrier

.LBB0_950:
	s_add_i32 s9, s26, 2
	s_add_u32 s60, s38, 0x100
	s_addc_u32 s61, s39, 0
	s_add_i32 s78, 0, 0x10000
	s_cmp_eq_u32 s29, s26
	s_cselect_b32 s73, s25, s61
	s_cselect_b32 s72, s24, s60
	s_cselect_b32 s27, s37, vcc_hi
	s_cselect_b32 s26, s36, vcc_lo
	s_add_i32 s79, 0, 0x14000
	v_add_u32_e32 v156, s78, v177
	v_add_u32_e32 v172, s79, v177
	ds_read_b128 v[140:143], v156
	ds_read_b128 v[144:147], v156 offset:1024
	ds_read_b128 v[148:151], v156 offset:2048
	ds_read_b128 v[156:159], v156 offset:3072
	ds_read_b128 v[160:163], v172
	ds_read_b128 v[164:167], v172 offset:1024
	ds_read_b128 v[168:171], v172 offset:2048
	ds_read_b128 v[172:175], v172 offset:3072
	v_lshl_add_u64 v[212:213], s[38:39], 0, v[136:137]
	s_add_i32 m0, s50, 0xc000
	ds_read_b128 v[180:183], v179
	ds_read_b128 v[184:187], v179 offset:1024
	ds_read_b128 v[188:191], v179 offset:2048
	ds_read_b128 v[192:195], v179 offset:3072
	ds_read_b128 v[196:199], v179 offset:4096
	ds_read_b128 v[200:203], v179 offset:5120
	ds_read_b128 v[204:207], v179 offset:6144
	ds_read_b128 v[208:211], v179 offset:7168
	global_load_lds_dwordx4 v[212:213], off
	s_add_i32 m0, s50, 0xe000
	v_lshl_add_u64 v[212:213], s[38:39], 0, v[138:139]
	global_load_lds_dwordx4 v[212:213], off
	s_waitcnt vmcnt(8)
	s_waitcnt lgkmcnt(0)
	s_setprio 1
	s_barrier
	v_mfma_f32_16x16x32_bf16 v[126:129], v[140:143], v[180:183], v[126:129]
	v_mfma_f32_16x16x32_bf16 v[122:125], v[148:151], v[180:183], v[122:125]
	v_mfma_f32_16x16x32_bf16 v[110:113], v[140:143], v[188:191], v[110:113]
	v_mfma_f32_16x16x32_bf16 v[106:109], v[148:151], v[188:191], v[106:109]
	v_mfma_f32_16x16x32_bf16 v[94:97], v[140:143], v[196:199], v[94:97]
	v_mfma_f32_16x16x32_bf16 v[90:93], v[148:151], v[196:199], v[90:93]
	v_mfma_f32_16x16x32_bf16 v[78:81], v[140:143], v[204:207], v[78:81]
	v_mfma_f32_16x16x32_bf16 v[74:77], v[148:151], v[204:207], v[74:77]
	v_mfma_f32_16x16x32_bf16 v[126:129], v[144:147], v[184:187], v[126:129]
	v_mfma_f32_16x16x32_bf16 v[122:125], v[156:159], v[184:187], v[122:125]
	v_mfma_f32_16x16x32_bf16 v[110:113], v[144:147], v[192:195], v[110:113]
	v_mfma_f32_16x16x32_bf16 v[106:109], v[156:159], v[192:195], v[106:109]
	v_mfma_f32_16x16x32_bf16 v[94:97], v[144:147], v[200:203], v[94:97]
	v_mfma_f32_16x16x32_bf16 v[90:93], v[156:159], v[200:203], v[90:93]
	v_mfma_f32_16x16x32_bf16 v[78:81], v[144:147], v[208:211], v[78:81]
	v_mfma_f32_16x16x32_bf16 v[74:77], v[156:159], v[208:211], v[74:77]
	v_mfma_f32_16x16x32_bf16 v[118:121], v[160:163], v[180:183], v[118:121]
	v_mfma_f32_16x16x32_bf16 v[114:117], v[168:171], v[180:183], v[114:117]
	v_mfma_f32_16x16x32_bf16 v[102:105], v[160:163], v[188:191], v[102:105]
	v_mfma_f32_16x16x32_bf16 v[98:101], v[168:171], v[188:191], v[98:101]
	v_mfma_f32_16x16x32_bf16 v[86:89], v[160:163], v[196:199], v[86:89]
	v_mfma_f32_16x16x32_bf16 v[82:85], v[168:171], v[196:199], v[82:85]
	v_mfma_f32_16x16x32_bf16 v[70:73], v[160:163], v[204:207], v[70:73]
	v_mfma_f32_16x16x32_bf16 v[66:69], v[168:171], v[204:207], v[66:69]
	v_mfma_f32_16x16x32_bf16 v[118:121], v[164:167], v[184:187], v[118:121]
	v_mfma_f32_16x16x32_bf16 v[114:117], v[172:175], v[184:187], v[114:117]
	v_mfma_f32_16x16x32_bf16 v[102:105], v[164:167], v[192:195], v[102:105]
	v_mfma_f32_16x16x32_bf16 v[98:101], v[172:175], v[192:195], v[98:101]
	v_mfma_f32_16x16x32_bf16 v[86:89], v[164:167], v[200:203], v[86:89]
	v_mfma_f32_16x16x32_bf16 v[82:85], v[172:175], v[200:203], v[82:85]
	v_mfma_f32_16x16x32_bf16 v[70:73], v[164:167], v[208:211], v[70:73]
	s_setprio 0
	v_mfma_f32_16x16x32_bf16 v[66:69], v[172:175], v[208:211], v[66:69]
	s_barrier
	s_add_i32 s38, s78, s49
	v_lshl_add_u64 v[212:213], s[26:27], 0, v[0:1]
	s_mov_b32 m0, s38
	ds_read_b128 v[180:183], v179 offset:16384
	ds_read_b128 v[184:187], v179 offset:17408
	ds_read_b128 v[188:191], v179 offset:18432
	ds_read_b128 v[192:195], v179 offset:19456
	ds_read_b128 v[196:199], v179 offset:20480
	ds_read_b128 v[200:203], v179 offset:21504
	ds_read_b128 v[204:207], v179 offset:22528
	ds_read_b128 v[208:211], v179 offset:23552
	global_load_lds_dwordx4 v[212:213], off
	s_add_i32 m0, s38, 0x2000
	s_add_u32 s38, s26, 0xb0000
	v_lshl_add_u64 v[214:215], s[26:27], 0, v[134:135]
	s_addc_u32 s39, s27, 0
	s_add_i32 s78, s79, s49
	global_load_lds_dwordx4 v[214:215], off
	v_lshl_add_u64 v[216:217], s[38:39], 0, v[0:1]
	s_mov_b32 m0, s78
	v_lshl_add_u64 v[218:219], s[72:73], 0, v[132:133]
	global_load_lds_dwordx4 v[216:217], off
	s_add_i32 m0, s78, 0x2000
	v_lshl_add_u64 v[216:217], s[38:39], 0, v[134:135]
	global_load_lds_dwordx4 v[216:217], off
	s_mov_b32 m0, s50
	v_lshl_add_u64 v[216:217], s[72:73], 0, v[130:131]
	global_load_lds_dwordx4 v[216:217], off
	s_mov_b32 m0, s51
	s_nop 0
	global_load_lds_dwordx4 v[218:219], off
	s_waitcnt vmcnt(8)
	s_waitcnt lgkmcnt(0)
	s_setprio 1
	s_barrier
	v_mfma_f32_16x16x32_bf16 v[62:65], v[140:143], v[180:183], v[62:65]
	v_mfma_f32_16x16x32_bf16 v[58:61], v[148:151], v[180:183], v[58:61]
	v_mfma_f32_16x16x32_bf16 v[46:49], v[140:143], v[188:191], v[46:49]
	v_mfma_f32_16x16x32_bf16 v[42:45], v[148:151], v[188:191], v[42:45]
	v_mfma_f32_16x16x32_bf16 v[30:33], v[140:143], v[196:199], v[30:33]
	v_mfma_f32_16x16x32_bf16 v[26:29], v[148:151], v[196:199], v[26:29]
	v_mfma_f32_16x16x32_bf16 v[14:17], v[140:143], v[204:207], v[14:17]
	v_mfma_f32_16x16x32_bf16 v[10:13], v[148:151], v[204:207], v[10:13]
	v_mfma_f32_16x16x32_bf16 v[62:65], v[144:147], v[184:187], v[62:65]
	v_mfma_f32_16x16x32_bf16 v[58:61], v[156:159], v[184:187], v[58:61]
	v_mfma_f32_16x16x32_bf16 v[46:49], v[144:147], v[192:195], v[46:49]
	v_mfma_f32_16x16x32_bf16 v[42:45], v[156:159], v[192:195], v[42:45]
	v_mfma_f32_16x16x32_bf16 v[30:33], v[144:147], v[200:203], v[30:33]
	v_mfma_f32_16x16x32_bf16 v[26:29], v[156:159], v[200:203], v[26:29]
	v_mfma_f32_16x16x32_bf16 v[14:17], v[144:147], v[208:211], v[14:17]
	v_mfma_f32_16x16x32_bf16 v[10:13], v[156:159], v[208:211], v[10:13]
	v_mfma_f32_16x16x32_bf16 v[54:57], v[160:163], v[180:183], v[54:57]
	v_mfma_f32_16x16x32_bf16 v[50:53], v[168:171], v[180:183], v[50:53]
	v_mfma_f32_16x16x32_bf16 v[38:41], v[160:163], v[188:191], v[38:41]
	v_mfma_f32_16x16x32_bf16 v[34:37], v[168:171], v[188:191], v[34:37]
	v_mfma_f32_16x16x32_bf16 v[22:25], v[160:163], v[196:199], v[22:25]
	v_mfma_f32_16x16x32_bf16 v[18:21], v[168:171], v[196:199], v[18:21]
	v_mfma_f32_16x16x32_bf16 v[6:9], v[160:163], v[204:207], v[6:9]
	v_mfma_f32_16x16x32_bf16 v[2:5], v[168:171], v[204:207], v[2:5]
	v_mfma_f32_16x16x32_bf16 v[54:57], v[164:167], v[184:187], v[54:57]
	v_mfma_f32_16x16x32_bf16 v[50:53], v[172:175], v[184:187], v[50:53]
	v_mfma_f32_16x16x32_bf16 v[38:41], v[164:167], v[192:195], v[38:41]
	v_mfma_f32_16x16x32_bf16 v[34:37], v[172:175], v[192:195], v[34:37]
	v_mfma_f32_16x16x32_bf16 v[22:25], v[164:167], v[200:203], v[22:25]
	v_mfma_f32_16x16x32_bf16 v[18:21], v[172:175], v[200:203], v[18:21]
	v_mfma_f32_16x16x32_bf16 v[6:9], v[164:167], v[208:211], v[6:9]
	s_setprio 0
	v_mfma_f32_16x16x32_bf16 v[2:5], v[172:175], v[208:211], v[2:5]
	s_barrier
	s_add_i32 s78, 0, 0x18000
	s_add_i32 s79, 0, 0x1c000
	v_add_u32_e32 v156, s78, v177
	v_add_u32_e32 v172, s79, v177
	ds_read_b128 v[140:143], v156
	ds_read_b128 v[144:147], v156 offset:1024
	ds_read_b128 v[148:151], v156 offset:2048
	ds_read_b128 v[156:159], v156 offset:3072
	ds_read_b128 v[160:163], v172
	ds_read_b128 v[164:167], v172 offset:1024
	ds_read_b128 v[168:171], v172 offset:2048
	ds_read_b128 v[172:175], v172 offset:3072
	s_add_u32 s38, s72, 0xb0000
	s_addc_u32 s39, s73, 0
	s_mov_b32 m0, s52
	v_lshl_add_u64 v[220:221], s[38:39], 0, v[130:131]
	ds_read_b128 v[180:183], v179 offset:32768
	ds_read_b128 v[184:187], v179 offset:33792
	ds_read_b128 v[188:191], v179 offset:34816
	ds_read_b128 v[192:195], v179 offset:35840
	ds_read_b128 v[196:199], v179 offset:36864
	ds_read_b128 v[200:203], v179 offset:37888
	ds_read_b128 v[204:207], v179 offset:38912
	ds_read_b128 v[208:211], v179 offset:39936
	global_load_lds_dwordx4 v[220:221], off
	s_mov_b32 m0, s53
	v_lshl_add_u64 v[220:221], s[38:39], 0, v[132:133]
	global_load_lds_dwordx4 v[220:221], off
	s_waitcnt vmcnt(8)
	s_waitcnt lgkmcnt(0)
	s_setprio 1
	s_barrier
	v_mfma_f32_16x16x32_bf16 v[126:129], v[140:143], v[180:183], v[126:129]
	v_mfma_f32_16x16x32_bf16 v[122:125], v[148:151], v[180:183], v[122:125]
	v_mfma_f32_16x16x32_bf16 v[110:113], v[140:143], v[188:191], v[110:113]
	v_mfma_f32_16x16x32_bf16 v[106:109], v[148:151], v[188:191], v[106:109]
	v_mfma_f32_16x16x32_bf16 v[94:97], v[140:143], v[196:199], v[94:97]
	v_mfma_f32_16x16x32_bf16 v[90:93], v[148:151], v[196:199], v[90:93]
	v_mfma_f32_16x16x32_bf16 v[78:81], v[140:143], v[204:207], v[78:81]
	v_mfma_f32_16x16x32_bf16 v[74:77], v[148:151], v[204:207], v[74:77]
	v_mfma_f32_16x16x32_bf16 v[126:129], v[144:147], v[184:187], v[126:129]
	v_mfma_f32_16x16x32_bf16 v[122:125], v[156:159], v[184:187], v[122:125]
	v_mfma_f32_16x16x32_bf16 v[110:113], v[144:147], v[192:195], v[110:113]
	v_mfma_f32_16x16x32_bf16 v[106:109], v[156:159], v[192:195], v[106:109]
	v_mfma_f32_16x16x32_bf16 v[94:97], v[144:147], v[200:203], v[94:97]
	v_mfma_f32_16x16x32_bf16 v[90:93], v[156:159], v[200:203], v[90:93]
	v_mfma_f32_16x16x32_bf16 v[78:81], v[144:147], v[208:211], v[78:81]
	v_mfma_f32_16x16x32_bf16 v[74:77], v[156:159], v[208:211], v[74:77]
	v_mfma_f32_16x16x32_bf16 v[118:121], v[160:163], v[180:183], v[118:121]
	v_mfma_f32_16x16x32_bf16 v[114:117], v[168:171], v[180:183], v[114:117]
	v_mfma_f32_16x16x32_bf16 v[102:105], v[160:163], v[188:191], v[102:105]
	v_mfma_f32_16x16x32_bf16 v[98:101], v[168:171], v[188:191], v[98:101]
	v_mfma_f32_16x16x32_bf16 v[86:89], v[160:163], v[196:199], v[86:89]
	v_mfma_f32_16x16x32_bf16 v[82:85], v[168:171], v[196:199], v[82:85]
	v_mfma_f32_16x16x32_bf16 v[70:73], v[160:163], v[204:207], v[70:73]
	v_mfma_f32_16x16x32_bf16 v[66:69], v[168:171], v[204:207], v[66:69]
	v_mfma_f32_16x16x32_bf16 v[118:121], v[164:167], v[184:187], v[118:121]
	v_mfma_f32_16x16x32_bf16 v[114:117], v[172:175], v[184:187], v[114:117]
	v_mfma_f32_16x16x32_bf16 v[102:105], v[164:167], v[192:195], v[102:105]
	v_mfma_f32_16x16x32_bf16 v[98:101], v[172:175], v[192:195], v[98:101]
	v_mfma_f32_16x16x32_bf16 v[86:89], v[164:167], v[200:203], v[86:89]
	v_mfma_f32_16x16x32_bf16 v[82:85], v[172:175], v[200:203], v[82:85]
	v_mfma_f32_16x16x32_bf16 v[70:73], v[164:167], v[208:211], v[70:73]
	s_setprio 0
	v_mfma_f32_16x16x32_bf16 v[66:69], v[172:175], v[208:211], v[66:69]
	s_barrier
	s_add_i32 s38, s78, s49
	v_lshl_add_u64 v[212:213], v[212:213], 0, s[70:71]
	s_mov_b32 m0, s38
	ds_read_b128 v[180:183], v179 offset:49152
	ds_read_b128 v[184:187], v179 offset:50176
	ds_read_b128 v[188:191], v179 offset:51200
	ds_read_b128 v[192:195], v179 offset:52224
	ds_read_b128 v[196:199], v179 offset:53248
	ds_read_b128 v[200:203], v179 offset:54272
	ds_read_b128 v[204:207], v179 offset:55296
	ds_read_b128 v[208:211], v179 offset:56320
	global_load_lds_dwordx4 v[212:213], off
	s_add_i32 m0, s38, 0x2000
	s_add_u32 s26, s26, 0xb0080
	v_lshl_add_u64 v[212:213], v[214:215], 0, s[70:71]
	s_addc_u32 s27, s27, 0
	s_add_i32 s38, s79, s49
	global_load_lds_dwordx4 v[212:213], off
	s_mov_b32 m0, s38
	v_lshl_add_u64 v[212:213], s[26:27], 0, v[0:1]
	global_load_lds_dwordx4 v[212:213], off
	s_add_i32 m0, s38, 0x2000
	v_lshl_add_u64 v[212:213], s[26:27], 0, v[134:135]
	global_load_lds_dwordx4 v[212:213], off
	s_mov_b32 m0, s74
	v_lshl_add_u64 v[212:213], v[216:217], 0, s[70:71]
	global_load_lds_dwordx4 v[212:213], off
	s_mov_b32 m0, s75
	v_lshl_add_u64 v[212:213], v[218:219], 0, s[70:71]
	global_load_lds_dwordx4 v[212:213], off
	s_waitcnt vmcnt(8)
	s_waitcnt lgkmcnt(0)
	s_setprio 1
	s_barrier
	v_mfma_f32_16x16x32_bf16 v[62:65], v[140:143], v[180:183], v[62:65]
	v_mfma_f32_16x16x32_bf16 v[58:61], v[148:151], v[180:183], v[58:61]
	v_mfma_f32_16x16x32_bf16 v[46:49], v[140:143], v[188:191], v[46:49]
	v_mfma_f32_16x16x32_bf16 v[42:45], v[148:151], v[188:191], v[42:45]
	v_mfma_f32_16x16x32_bf16 v[30:33], v[140:143], v[196:199], v[30:33]
	v_mfma_f32_16x16x32_bf16 v[26:29], v[148:151], v[196:199], v[26:29]
	v_mfma_f32_16x16x32_bf16 v[14:17], v[140:143], v[204:207], v[14:17]
	v_mfma_f32_16x16x32_bf16 v[10:13], v[148:151], v[204:207], v[10:13]
	v_mfma_f32_16x16x32_bf16 v[62:65], v[144:147], v[184:187], v[62:65]
	v_mfma_f32_16x16x32_bf16 v[58:61], v[156:159], v[184:187], v[58:61]
	v_mfma_f32_16x16x32_bf16 v[46:49], v[144:147], v[192:195], v[46:49]
	v_mfma_f32_16x16x32_bf16 v[42:45], v[156:159], v[192:195], v[42:45]
	v_mfma_f32_16x16x32_bf16 v[30:33], v[144:147], v[200:203], v[30:33]
	v_mfma_f32_16x16x32_bf16 v[26:29], v[156:159], v[200:203], v[26:29]
	v_mfma_f32_16x16x32_bf16 v[14:17], v[144:147], v[208:211], v[14:17]
	v_mfma_f32_16x16x32_bf16 v[10:13], v[156:159], v[208:211], v[10:13]
	v_mfma_f32_16x16x32_bf16 v[54:57], v[160:163], v[180:183], v[54:57]
	v_mfma_f32_16x16x32_bf16 v[50:53], v[168:171], v[180:183], v[50:53]
	v_mfma_f32_16x16x32_bf16 v[38:41], v[160:163], v[188:191], v[38:41]
	v_mfma_f32_16x16x32_bf16 v[34:37], v[168:171], v[188:191], v[34:37]
	v_mfma_f32_16x16x32_bf16 v[22:25], v[160:163], v[196:199], v[22:25]
	v_mfma_f32_16x16x32_bf16 v[18:21], v[168:171], v[196:199], v[18:21]
	v_mfma_f32_16x16x32_bf16 v[6:9], v[160:163], v[204:207], v[6:9]
	v_mfma_f32_16x16x32_bf16 v[2:5], v[168:171], v[204:207], v[2:5]
	v_mfma_f32_16x16x32_bf16 v[54:57], v[164:167], v[184:187], v[54:57]
	v_mfma_f32_16x16x32_bf16 v[50:53], v[172:175], v[184:187], v[50:53]
	v_mfma_f32_16x16x32_bf16 v[38:41], v[164:167], v[192:195], v[38:41]
	v_mfma_f32_16x16x32_bf16 v[34:37], v[172:175], v[192:195], v[34:37]
	v_mfma_f32_16x16x32_bf16 v[22:25], v[164:167], v[200:203], v[22:25]
	v_mfma_f32_16x16x32_bf16 v[18:21], v[172:175], v[200:203], v[18:21]
	v_mfma_f32_16x16x32_bf16 v[6:9], v[164:167], v[208:211], v[6:9]
	s_setprio 0
	v_mfma_f32_16x16x32_bf16 v[2:5], v[172:175], v[208:211], v[2:5]
	s_barrier
	s_add_u32 vcc_lo, vcc_lo, 0x100
	s_addc_u32 vcc_hi, vcc_hi, 0
	s_cmp_ge_u32 s9, s28
	s_mov_b64 s[38:39], s[60:61]
	s_mov_b32 s26, s9
	s_cbranch_scc0 .LBB0_950
	s_and_b64 vcc, exec, s[22:23]
	s_cbranch_vccz .LBB0_953

.LBB0_1000:
	s_add_i32 s9, s26, 2
	s_add_u32 s60, s38, 0x100
	s_addc_u32 s61, s39, 0
	s_add_i32 s78, 0, 0x10000
	s_cmp_eq_u32 s29, s26
	s_cselect_b32 s73, s25, s61
	s_cselect_b32 s72, s24, s60
	v_add_u32_e32 v148, s78, v251
	s_cselect_b32 s27, s37, vcc_hi
	s_cselect_b32 s26, s36, vcc_lo
	s_add_i32 s79, 0, 0x14000
	ds_read_b128 v[140:143], v148
	ds_read_b128 v[144:147], v148 offset:1024
	ds_read_b128 v[156:159], v148 offset:2048
	ds_read_b128 v[160:163], v148 offset:3072
	v_add_u32_e32 v148, s79, v251
	ds_read_b128 v[164:167], v148
	ds_read_b128 v[168:171], v148 offset:1024
	ds_read_b128 v[172:175], v148 offset:2048
	ds_read_b128 v[176:179], v148 offset:3072
	v_lshl_add_u64 v[148:149], s[38:39], 0, v[136:137]
	s_add_i32 m0, s50, 0xc000
	ds_read_b128 v[180:183], v253
	ds_read_b128 v[184:187], v253 offset:1024
	ds_read_b128 v[188:191], v253 offset:2048
	ds_read_b128 v[192:195], v253 offset:3072
	ds_read_b128 v[196:199], v253 offset:4096
	ds_read_b128 v[200:203], v253 offset:5120
	ds_read_b128 v[204:207], v253 offset:6144
	ds_read_b128 v[208:211], v253 offset:7168
	global_load_lds_dwordx4 v[148:149], off
	s_add_i32 m0, s50, 0xe000
	v_lshl_add_u64 v[148:149], s[38:39], 0, v[138:139]
	global_load_lds_dwordx4 v[148:149], off
	s_waitcnt vmcnt(8)
	s_waitcnt lgkmcnt(0)
	s_setprio 1
	s_barrier
	v_mfma_f32_16x16x32_bf16 v[126:129], v[140:143], v[180:183], v[126:129]
	v_mfma_f32_16x16x32_bf16 v[122:125], v[156:159], v[180:183], v[122:125]
	v_mfma_f32_16x16x32_bf16 v[110:113], v[140:143], v[188:191], v[110:113]
	v_mfma_f32_16x16x32_bf16 v[106:109], v[156:159], v[188:191], v[106:109]
	v_mfma_f32_16x16x32_bf16 v[94:97], v[140:143], v[196:199], v[94:97]
	v_mfma_f32_16x16x32_bf16 v[90:93], v[156:159], v[196:199], v[90:93]
	v_mfma_f32_16x16x32_bf16 v[78:81], v[140:143], v[204:207], v[78:81]
	v_mfma_f32_16x16x32_bf16 v[74:77], v[156:159], v[204:207], v[74:77]
	v_mfma_f32_16x16x32_bf16 v[126:129], v[144:147], v[184:187], v[126:129]
	v_mfma_f32_16x16x32_bf16 v[122:125], v[160:163], v[184:187], v[122:125]
	v_mfma_f32_16x16x32_bf16 v[110:113], v[144:147], v[192:195], v[110:113]
	v_mfma_f32_16x16x32_bf16 v[106:109], v[160:163], v[192:195], v[106:109]
	v_mfma_f32_16x16x32_bf16 v[94:97], v[144:147], v[200:203], v[94:97]
	v_mfma_f32_16x16x32_bf16 v[90:93], v[160:163], v[200:203], v[90:93]
	v_mfma_f32_16x16x32_bf16 v[78:81], v[144:147], v[208:211], v[78:81]
	v_mfma_f32_16x16x32_bf16 v[74:77], v[160:163], v[208:211], v[74:77]
	v_mfma_f32_16x16x32_bf16 v[118:121], v[164:167], v[180:183], v[118:121]
	v_mfma_f32_16x16x32_bf16 v[114:117], v[172:175], v[180:183], v[114:117]
	v_mfma_f32_16x16x32_bf16 v[102:105], v[164:167], v[188:191], v[102:105]
	v_mfma_f32_16x16x32_bf16 v[98:101], v[172:175], v[188:191], v[98:101]
	v_mfma_f32_16x16x32_bf16 v[86:89], v[164:167], v[196:199], v[86:89]
	v_mfma_f32_16x16x32_bf16 v[82:85], v[172:175], v[196:199], v[82:85]
	v_mfma_f32_16x16x32_bf16 v[70:73], v[164:167], v[204:207], v[70:73]
	v_mfma_f32_16x16x32_bf16 v[66:69], v[172:175], v[204:207], v[66:69]
	v_mfma_f32_16x16x32_bf16 v[118:121], v[168:171], v[184:187], v[118:121]
	v_mfma_f32_16x16x32_bf16 v[114:117], v[176:179], v[184:187], v[114:117]
	v_mfma_f32_16x16x32_bf16 v[102:105], v[168:171], v[192:195], v[102:105]
	v_mfma_f32_16x16x32_bf16 v[98:101], v[176:179], v[192:195], v[98:101]
	v_mfma_f32_16x16x32_bf16 v[86:89], v[168:171], v[200:203], v[86:89]
	v_mfma_f32_16x16x32_bf16 v[82:85], v[176:179], v[200:203], v[82:85]
	v_mfma_f32_16x16x32_bf16 v[70:73], v[168:171], v[208:211], v[70:73]
	s_setprio 0
	v_mfma_f32_16x16x32_bf16 v[66:69], v[176:179], v[208:211], v[66:69]
	s_barrier
	s_add_i32 s38, s78, s49
	v_lshl_add_u64 v[148:149], s[26:27], 0, v[0:1]
	s_mov_b32 m0, s38
	ds_read_b128 v[180:183], v253 offset:16384
	ds_read_b128 v[184:187], v253 offset:17408
	ds_read_b128 v[188:191], v253 offset:18432
	ds_read_b128 v[192:195], v253 offset:19456
	ds_read_b128 v[196:199], v253 offset:20480
	ds_read_b128 v[200:203], v253 offset:21504
	ds_read_b128 v[204:207], v253 offset:22528
	ds_read_b128 v[208:211], v253 offset:23552
	global_load_lds_dwordx4 v[148:149], off
	s_add_i32 m0, s38, 0x2000
	s_add_u32 s38, s26, 0xb0000
	v_lshl_add_u64 v[150:151], s[26:27], 0, v[134:135]
	s_addc_u32 s39, s27, 0
	s_add_i32 s78, s79, s49
	global_load_lds_dwordx4 v[150:151], off
	v_lshl_add_u64 v[212:213], s[38:39], 0, v[0:1]
	s_mov_b32 m0, s78
	v_lshl_add_u64 v[214:215], s[72:73], 0, v[132:133]
	global_load_lds_dwordx4 v[212:213], off
	s_add_i32 m0, s78, 0x2000
	v_lshl_add_u64 v[212:213], s[38:39], 0, v[134:135]
	global_load_lds_dwordx4 v[212:213], off
	s_mov_b32 m0, s50
	v_lshl_add_u64 v[212:213], s[72:73], 0, v[130:131]
	global_load_lds_dwordx4 v[212:213], off
	s_mov_b32 m0, s51
	s_nop 0
	global_load_lds_dwordx4 v[214:215], off
	s_waitcnt vmcnt(8)
	s_waitcnt lgkmcnt(0)
	s_setprio 1
	s_barrier
	v_mfma_f32_16x16x32_bf16 v[62:65], v[140:143], v[180:183], v[62:65]
	v_mfma_f32_16x16x32_bf16 v[58:61], v[156:159], v[180:183], v[58:61]
	v_mfma_f32_16x16x32_bf16 v[46:49], v[140:143], v[188:191], v[46:49]
	v_mfma_f32_16x16x32_bf16 v[42:45], v[156:159], v[188:191], v[42:45]
	v_mfma_f32_16x16x32_bf16 v[30:33], v[140:143], v[196:199], v[30:33]
	v_mfma_f32_16x16x32_bf16 v[26:29], v[156:159], v[196:199], v[26:29]
	v_mfma_f32_16x16x32_bf16 v[14:17], v[140:143], v[204:207], v[14:17]
	v_mfma_f32_16x16x32_bf16 v[10:13], v[156:159], v[204:207], v[10:13]
	v_mfma_f32_16x16x32_bf16 v[62:65], v[144:147], v[184:187], v[62:65]
	v_mfma_f32_16x16x32_bf16 v[58:61], v[160:163], v[184:187], v[58:61]
	v_mfma_f32_16x16x32_bf16 v[46:49], v[144:147], v[192:195], v[46:49]
	v_mfma_f32_16x16x32_bf16 v[42:45], v[160:163], v[192:195], v[42:45]
	v_mfma_f32_16x16x32_bf16 v[30:33], v[144:147], v[200:203], v[30:33]
	v_mfma_f32_16x16x32_bf16 v[26:29], v[160:163], v[200:203], v[26:29]
	v_mfma_f32_16x16x32_bf16 v[14:17], v[144:147], v[208:211], v[14:17]
	v_mfma_f32_16x16x32_bf16 v[10:13], v[160:163], v[208:211], v[10:13]
	v_mfma_f32_16x16x32_bf16 v[54:57], v[164:167], v[180:183], v[54:57]
	v_mfma_f32_16x16x32_bf16 v[50:53], v[172:175], v[180:183], v[50:53]
	v_mfma_f32_16x16x32_bf16 v[38:41], v[164:167], v[188:191], v[38:41]
	v_mfma_f32_16x16x32_bf16 v[34:37], v[172:175], v[188:191], v[34:37]
	v_mfma_f32_16x16x32_bf16 v[22:25], v[164:167], v[196:199], v[22:25]
	v_mfma_f32_16x16x32_bf16 v[18:21], v[172:175], v[196:199], v[18:21]
	v_mfma_f32_16x16x32_bf16 v[6:9], v[164:167], v[204:207], v[6:9]
	v_mfma_f32_16x16x32_bf16 v[2:5], v[172:175], v[204:207], v[2:5]
	v_mfma_f32_16x16x32_bf16 v[54:57], v[168:171], v[184:187], v[54:57]
	v_mfma_f32_16x16x32_bf16 v[50:53], v[176:179], v[184:187], v[50:53]
	v_mfma_f32_16x16x32_bf16 v[38:41], v[168:171], v[192:195], v[38:41]
	v_mfma_f32_16x16x32_bf16 v[34:37], v[176:179], v[192:195], v[34:37]
	v_mfma_f32_16x16x32_bf16 v[22:25], v[168:171], v[200:203], v[22:25]
	v_mfma_f32_16x16x32_bf16 v[18:21], v[176:179], v[200:203], v[18:21]
	v_mfma_f32_16x16x32_bf16 v[6:9], v[168:171], v[208:211], v[6:9]
	s_setprio 0
	v_mfma_f32_16x16x32_bf16 v[2:5], v[176:179], v[208:211], v[2:5]
	s_barrier
	s_add_i32 s78, 0, 0x18000
	s_add_i32 s79, 0, 0x1c000
	v_add_u32_e32 v160, s78, v251
	v_add_u32_e32 v176, s79, v251
	ds_read_b128 v[140:143], v160
	ds_read_b128 v[144:147], v160 offset:1024
	ds_read_b128 v[156:159], v160 offset:2048
	ds_read_b128 v[160:163], v160 offset:3072
	ds_read_b128 v[164:167], v176
	ds_read_b128 v[168:171], v176 offset:1024
	ds_read_b128 v[172:175], v176 offset:2048
	ds_read_b128 v[176:179], v176 offset:3072
	s_add_u32 s38, s72, 0xb0000
	s_addc_u32 s39, s73, 0
	s_mov_b32 m0, s52
	v_lshl_add_u64 v[216:217], s[38:39], 0, v[130:131]
	ds_read_b128 v[180:183], v253 offset:32768
	ds_read_b128 v[184:187], v253 offset:33792
	ds_read_b128 v[188:191], v253 offset:34816
	ds_read_b128 v[192:195], v253 offset:35840
	ds_read_b128 v[196:199], v253 offset:36864
	ds_read_b128 v[200:203], v253 offset:37888
	ds_read_b128 v[204:207], v253 offset:38912
	ds_read_b128 v[208:211], v253 offset:39936
	global_load_lds_dwordx4 v[216:217], off
	s_mov_b32 m0, s53
	v_lshl_add_u64 v[216:217], s[38:39], 0, v[132:133]
	global_load_lds_dwordx4 v[216:217], off
	s_waitcnt vmcnt(8)
	s_waitcnt lgkmcnt(0)
	s_setprio 1
	s_barrier
	v_mfma_f32_16x16x32_bf16 v[126:129], v[140:143], v[180:183], v[126:129]
	v_mfma_f32_16x16x32_bf16 v[122:125], v[156:159], v[180:183], v[122:125]
	v_mfma_f32_16x16x32_bf16 v[110:113], v[140:143], v[188:191], v[110:113]
	v_mfma_f32_16x16x32_bf16 v[106:109], v[156:159], v[188:191], v[106:109]
	v_mfma_f32_16x16x32_bf16 v[94:97], v[140:143], v[196:199], v[94:97]
	v_mfma_f32_16x16x32_bf16 v[90:93], v[156:159], v[196:199], v[90:93]
	v_mfma_f32_16x16x32_bf16 v[78:81], v[140:143], v[204:207], v[78:81]
	v_mfma_f32_16x16x32_bf16 v[74:77], v[156:159], v[204:207], v[74:77]
	v_mfma_f32_16x16x32_bf16 v[126:129], v[144:147], v[184:187], v[126:129]
	v_mfma_f32_16x16x32_bf16 v[122:125], v[160:163], v[184:187], v[122:125]
	v_mfma_f32_16x16x32_bf16 v[110:113], v[144:147], v[192:195], v[110:113]
	v_mfma_f32_16x16x32_bf16 v[106:109], v[160:163], v[192:195], v[106:109]
	v_mfma_f32_16x16x32_bf16 v[94:97], v[144:147], v[200:203], v[94:97]
	v_mfma_f32_16x16x32_bf16 v[90:93], v[160:163], v[200:203], v[90:93]
	v_mfma_f32_16x16x32_bf16 v[78:81], v[144:147], v[208:211], v[78:81]
	v_mfma_f32_16x16x32_bf16 v[74:77], v[160:163], v[208:211], v[74:77]
	v_mfma_f32_16x16x32_bf16 v[118:121], v[164:167], v[180:183], v[118:121]
	v_mfma_f32_16x16x32_bf16 v[114:117], v[172:175], v[180:183], v[114:117]
	v_mfma_f32_16x16x32_bf16 v[102:105], v[164:167], v[188:191], v[102:105]
	v_mfma_f32_16x16x32_bf16 v[98:101], v[172:175], v[188:191], v[98:101]
	v_mfma_f32_16x16x32_bf16 v[86:89], v[164:167], v[196:199], v[86:89]
	v_mfma_f32_16x16x32_bf16 v[82:85], v[172:175], v[196:199], v[82:85]
	v_mfma_f32_16x16x32_bf16 v[70:73], v[164:167], v[204:207], v[70:73]
	v_mfma_f32_16x16x32_bf16 v[66:69], v[172:175], v[204:207], v[66:69]
	v_mfma_f32_16x16x32_bf16 v[118:121], v[168:171], v[184:187], v[118:121]
	v_mfma_f32_16x16x32_bf16 v[114:117], v[176:179], v[184:187], v[114:117]
	v_mfma_f32_16x16x32_bf16 v[102:105], v[168:171], v[192:195], v[102:105]
	v_mfma_f32_16x16x32_bf16 v[98:101], v[176:179], v[192:195], v[98:101]
	v_mfma_f32_16x16x32_bf16 v[86:89], v[168:171], v[200:203], v[86:89]
	v_mfma_f32_16x16x32_bf16 v[82:85], v[176:179], v[200:203], v[82:85]
	v_mfma_f32_16x16x32_bf16 v[70:73], v[168:171], v[208:211], v[70:73]
	s_setprio 0
	v_mfma_f32_16x16x32_bf16 v[66:69], v[176:179], v[208:211], v[66:69]
	s_barrier
	s_add_i32 s38, s78, s49
	v_lshl_add_u64 v[148:149], v[148:149], 0, s[70:71]
	s_mov_b32 m0, s38
	ds_read_b128 v[180:183], v253 offset:49152
	ds_read_b128 v[184:187], v253 offset:50176
	ds_read_b128 v[188:191], v253 offset:51200
	ds_read_b128 v[192:195], v253 offset:52224
	ds_read_b128 v[196:199], v253 offset:53248
	ds_read_b128 v[200:203], v253 offset:54272
	ds_read_b128 v[204:207], v253 offset:55296
	ds_read_b128 v[208:211], v253 offset:56320
	global_load_lds_dwordx4 v[148:149], off
	s_add_i32 m0, s38, 0x2000
	s_add_u32 s26, s26, 0xb0080
	v_lshl_add_u64 v[148:149], v[150:151], 0, s[70:71]
	s_addc_u32 s27, s27, 0
	s_add_i32 s38, s79, s49
	global_load_lds_dwordx4 v[148:149], off
	s_mov_b32 m0, s38
	v_lshl_add_u64 v[148:149], s[26:27], 0, v[0:1]
	global_load_lds_dwordx4 v[148:149], off
	s_add_i32 m0, s38, 0x2000
	v_lshl_add_u64 v[148:149], s[26:27], 0, v[134:135]
	global_load_lds_dwordx4 v[148:149], off
	s_mov_b32 m0, s74
	v_lshl_add_u64 v[148:149], v[212:213], 0, s[70:71]
	global_load_lds_dwordx4 v[148:149], off
	s_mov_b32 m0, s75
	v_lshl_add_u64 v[148:149], v[214:215], 0, s[70:71]
	global_load_lds_dwordx4 v[148:149], off
	s_waitcnt vmcnt(8)
	s_waitcnt lgkmcnt(0)
	s_setprio 1
	s_barrier
	v_mfma_f32_16x16x32_bf16 v[62:65], v[140:143], v[180:183], v[62:65]
	v_mfma_f32_16x16x32_bf16 v[58:61], v[156:159], v[180:183], v[58:61]
	v_mfma_f32_16x16x32_bf16 v[46:49], v[140:143], v[188:191], v[46:49]
	v_mfma_f32_16x16x32_bf16 v[42:45], v[156:159], v[188:191], v[42:45]
	v_mfma_f32_16x16x32_bf16 v[30:33], v[140:143], v[196:199], v[30:33]
	v_mfma_f32_16x16x32_bf16 v[26:29], v[156:159], v[196:199], v[26:29]
	v_mfma_f32_16x16x32_bf16 v[14:17], v[140:143], v[204:207], v[14:17]
	v_mfma_f32_16x16x32_bf16 v[10:13], v[156:159], v[204:207], v[10:13]
	v_mfma_f32_16x16x32_bf16 v[62:65], v[144:147], v[184:187], v[62:65]
	v_mfma_f32_16x16x32_bf16 v[58:61], v[160:163], v[184:187], v[58:61]
	v_mfma_f32_16x16x32_bf16 v[46:49], v[144:147], v[192:195], v[46:49]
	v_mfma_f32_16x16x32_bf16 v[42:45], v[160:163], v[192:195], v[42:45]
	v_mfma_f32_16x16x32_bf16 v[30:33], v[144:147], v[200:203], v[30:33]
	v_mfma_f32_16x16x32_bf16 v[26:29], v[160:163], v[200:203], v[26:29]
	v_mfma_f32_16x16x32_bf16 v[14:17], v[144:147], v[208:211], v[14:17]
	v_mfma_f32_16x16x32_bf16 v[10:13], v[160:163], v[208:211], v[10:13]
	v_mfma_f32_16x16x32_bf16 v[54:57], v[164:167], v[180:183], v[54:57]
	v_mfma_f32_16x16x32_bf16 v[50:53], v[172:175], v[180:183], v[50:53]
	v_mfma_f32_16x16x32_bf16 v[38:41], v[164:167], v[188:191], v[38:41]
	v_mfma_f32_16x16x32_bf16 v[34:37], v[172:175], v[188:191], v[34:37]
	v_mfma_f32_16x16x32_bf16 v[22:25], v[164:167], v[196:199], v[22:25]
	v_mfma_f32_16x16x32_bf16 v[18:21], v[172:175], v[196:199], v[18:21]
	v_mfma_f32_16x16x32_bf16 v[6:9], v[164:167], v[204:207], v[6:9]
	v_mfma_f32_16x16x32_bf16 v[2:5], v[172:175], v[204:207], v[2:5]
	v_mfma_f32_16x16x32_bf16 v[54:57], v[168:171], v[184:187], v[54:57]
	v_mfma_f32_16x16x32_bf16 v[50:53], v[176:179], v[184:187], v[50:53]
	v_mfma_f32_16x16x32_bf16 v[38:41], v[168:171], v[192:195], v[38:41]
	v_mfma_f32_16x16x32_bf16 v[34:37], v[176:179], v[192:195], v[34:37]
	v_mfma_f32_16x16x32_bf16 v[22:25], v[168:171], v[200:203], v[22:25]
	v_mfma_f32_16x16x32_bf16 v[18:21], v[176:179], v[200:203], v[18:21]
	v_mfma_f32_16x16x32_bf16 v[6:9], v[168:171], v[208:211], v[6:9]
	s_setprio 0
	v_mfma_f32_16x16x32_bf16 v[2:5], v[176:179], v[208:211], v[2:5]
	s_barrier
	s_add_u32 vcc_lo, vcc_lo, 0x100
	s_addc_u32 vcc_hi, vcc_hi, 0
	s_cmp_ge_u32 s9, s28
	s_mov_b64 s[38:39], s[60:61]
	s_mov_b32 s26, s9
	s_cbranch_scc0 .LBB0_1000
	s_and_b64 vcc, exec, s[22:23]
	s_cbranch_vccz .LBB0_1003

.LBB0_1054:
	s_add_i32 s96, s26, 2
	s_add_u32 s36, s24, 0x100
	s_addc_u32 s37, s25, 0
	s_add_i32 s9, 0, 0x10000
	s_cmp_eq_u32 s93, s26
	s_cselect_b32 s39, s15, s37
	s_cselect_b32 s38, s14, s36
	v_add_u32_e32 v148, s9, v177
	s_cselect_b32 s27, s23, s95
	s_cselect_b32 s26, s22, s94
	s_add_i32 s78, 0, 0x14000
	ds_read_b128 v[140:143], v148
	ds_read_b128 v[144:147], v148 offset:1024
	ds_read_b128 v[156:159], v148 offset:2048
	ds_read_b128 v[160:163], v148 offset:3072
	v_add_u32_e32 v148, s78, v177
	ds_read_b128 v[164:167], v148
	ds_read_b128 v[168:171], v148 offset:1024
	ds_read_b128 v[172:175], v148 offset:2048
	ds_read_b128 v[180:183], v148 offset:3072
	v_lshl_add_u64 v[148:149], s[24:25], 0, v[136:137]
	s_add_i32 m0, s29, 0xc000
	ds_read_b128 v[184:187], v179
	ds_read_b128 v[188:191], v179 offset:1024
	ds_read_b128 v[192:195], v179 offset:2048
	ds_read_b128 v[196:199], v179 offset:3072
	ds_read_b128 v[200:203], v179 offset:4096
	ds_read_b128 v[204:207], v179 offset:5120
	ds_read_b128 v[208:211], v179 offset:6144
	ds_read_b128 v[212:215], v179 offset:7168
	global_load_lds_dwordx4 v[148:149], off
	s_add_i32 m0, s29, 0xe000
	v_lshl_add_u64 v[148:149], s[24:25], 0, v[138:139]
	global_load_lds_dwordx4 v[148:149], off
	s_waitcnt vmcnt(8)
	s_waitcnt lgkmcnt(0)
	s_setprio 1
	s_barrier
	v_mfma_f32_16x16x32_bf16 v[126:129], v[140:143], v[184:187], v[126:129]
	v_mfma_f32_16x16x32_bf16 v[122:125], v[156:159], v[184:187], v[122:125]
	v_mfma_f32_16x16x32_bf16 v[110:113], v[140:143], v[192:195], v[110:113]
	v_mfma_f32_16x16x32_bf16 v[106:109], v[156:159], v[192:195], v[106:109]
	v_mfma_f32_16x16x32_bf16 v[94:97], v[140:143], v[200:203], v[94:97]
	v_mfma_f32_16x16x32_bf16 v[90:93], v[156:159], v[200:203], v[90:93]
	v_mfma_f32_16x16x32_bf16 v[78:81], v[140:143], v[208:211], v[78:81]
	v_mfma_f32_16x16x32_bf16 v[74:77], v[156:159], v[208:211], v[74:77]
	v_mfma_f32_16x16x32_bf16 v[126:129], v[144:147], v[188:191], v[126:129]
	v_mfma_f32_16x16x32_bf16 v[122:125], v[160:163], v[188:191], v[122:125]
	v_mfma_f32_16x16x32_bf16 v[110:113], v[144:147], v[196:199], v[110:113]
	v_mfma_f32_16x16x32_bf16 v[106:109], v[160:163], v[196:199], v[106:109]
	v_mfma_f32_16x16x32_bf16 v[94:97], v[144:147], v[204:207], v[94:97]
	v_mfma_f32_16x16x32_bf16 v[90:93], v[160:163], v[204:207], v[90:93]
	v_mfma_f32_16x16x32_bf16 v[78:81], v[144:147], v[212:215], v[78:81]
	v_mfma_f32_16x16x32_bf16 v[74:77], v[160:163], v[212:215], v[74:77]
	v_mfma_f32_16x16x32_bf16 v[118:121], v[164:167], v[184:187], v[118:121]
	v_mfma_f32_16x16x32_bf16 v[114:117], v[172:175], v[184:187], v[114:117]
	v_mfma_f32_16x16x32_bf16 v[102:105], v[164:167], v[192:195], v[102:105]
	v_mfma_f32_16x16x32_bf16 v[98:101], v[172:175], v[192:195], v[98:101]
	v_mfma_f32_16x16x32_bf16 v[86:89], v[164:167], v[200:203], v[86:89]
	v_mfma_f32_16x16x32_bf16 v[82:85], v[172:175], v[200:203], v[82:85]
	v_mfma_f32_16x16x32_bf16 v[70:73], v[164:167], v[208:211], v[70:73]
	v_mfma_f32_16x16x32_bf16 v[66:69], v[172:175], v[208:211], v[66:69]
	v_mfma_f32_16x16x32_bf16 v[118:121], v[168:171], v[188:191], v[118:121]
	v_mfma_f32_16x16x32_bf16 v[114:117], v[180:183], v[188:191], v[114:117]
	v_mfma_f32_16x16x32_bf16 v[102:105], v[168:171], v[196:199], v[102:105]
	v_mfma_f32_16x16x32_bf16 v[98:101], v[180:183], v[196:199], v[98:101]
	v_mfma_f32_16x16x32_bf16 v[86:89], v[168:171], v[204:207], v[86:89]
	v_mfma_f32_16x16x32_bf16 v[82:85], v[180:183], v[204:207], v[82:85]
	v_mfma_f32_16x16x32_bf16 v[70:73], v[168:171], v[212:215], v[70:73]
	s_setprio 0
	v_mfma_f32_16x16x32_bf16 v[66:69], v[180:183], v[212:215], v[66:69]
	s_barrier
	s_add_i32 s9, s9, s28
	v_lshl_add_u64 v[148:149], s[26:27], 0, v[0:1]
	s_mov_b32 m0, s9
	ds_read_b128 v[184:187], v179 offset:16384
	ds_read_b128 v[188:191], v179 offset:17408
	ds_read_b128 v[192:195], v179 offset:18432
	ds_read_b128 v[196:199], v179 offset:19456
	ds_read_b128 v[200:203], v179 offset:20480
	ds_read_b128 v[204:207], v179 offset:21504
	ds_read_b128 v[208:211], v179 offset:22528
	ds_read_b128 v[212:215], v179 offset:23552
	global_load_lds_dwordx4 v[148:149], off
	s_add_i32 m0, s9, 0x2000
	s_add_u32 s24, s26, 0xb0000
	v_lshl_add_u64 v[150:151], s[26:27], 0, v[134:135]
	s_addc_u32 s25, s27, 0
	s_add_i32 s9, s78, s28
	global_load_lds_dwordx4 v[150:151], off
	v_lshl_add_u64 v[216:217], s[24:25], 0, v[0:1]
	s_mov_b32 m0, s9
	v_lshl_add_u64 v[218:219], s[38:39], 0, v[132:133]
	global_load_lds_dwordx4 v[216:217], off
	s_add_i32 m0, s9, 0x2000
	v_lshl_add_u64 v[216:217], s[24:25], 0, v[134:135]
	global_load_lds_dwordx4 v[216:217], off
	s_mov_b32 m0, s29
	v_lshl_add_u64 v[216:217], s[38:39], 0, v[130:131]
	global_load_lds_dwordx4 v[216:217], off
	s_mov_b32 m0, s49
	s_nop 0
	global_load_lds_dwordx4 v[218:219], off
	s_waitcnt vmcnt(8)
	s_waitcnt lgkmcnt(0)
	s_setprio 1
	s_barrier
	v_mfma_f32_16x16x32_bf16 v[62:65], v[140:143], v[184:187], v[62:65]
	v_mfma_f32_16x16x32_bf16 v[58:61], v[156:159], v[184:187], v[58:61]
	v_mfma_f32_16x16x32_bf16 v[46:49], v[140:143], v[192:195], v[46:49]
	v_mfma_f32_16x16x32_bf16 v[42:45], v[156:159], v[192:195], v[42:45]
	v_mfma_f32_16x16x32_bf16 v[30:33], v[140:143], v[200:203], v[30:33]
	v_mfma_f32_16x16x32_bf16 v[26:29], v[156:159], v[200:203], v[26:29]
	v_mfma_f32_16x16x32_bf16 v[14:17], v[140:143], v[208:211], v[14:17]
	v_mfma_f32_16x16x32_bf16 v[10:13], v[156:159], v[208:211], v[10:13]
	v_mfma_f32_16x16x32_bf16 v[62:65], v[144:147], v[188:191], v[62:65]
	v_mfma_f32_16x16x32_bf16 v[58:61], v[160:163], v[188:191], v[58:61]
	v_mfma_f32_16x16x32_bf16 v[46:49], v[144:147], v[196:199], v[46:49]
	v_mfma_f32_16x16x32_bf16 v[42:45], v[160:163], v[196:199], v[42:45]
	v_mfma_f32_16x16x32_bf16 v[30:33], v[144:147], v[204:207], v[30:33]
	v_mfma_f32_16x16x32_bf16 v[26:29], v[160:163], v[204:207], v[26:29]
	v_mfma_f32_16x16x32_bf16 v[14:17], v[144:147], v[212:215], v[14:17]
	v_mfma_f32_16x16x32_bf16 v[10:13], v[160:163], v[212:215], v[10:13]
	v_mfma_f32_16x16x32_bf16 v[54:57], v[164:167], v[184:187], v[54:57]
	v_mfma_f32_16x16x32_bf16 v[50:53], v[172:175], v[184:187], v[50:53]
	v_mfma_f32_16x16x32_bf16 v[38:41], v[164:167], v[192:195], v[38:41]
	v_mfma_f32_16x16x32_bf16 v[34:37], v[172:175], v[192:195], v[34:37]
	v_mfma_f32_16x16x32_bf16 v[22:25], v[164:167], v[200:203], v[22:25]
	v_mfma_f32_16x16x32_bf16 v[18:21], v[172:175], v[200:203], v[18:21]
	v_mfma_f32_16x16x32_bf16 v[6:9], v[164:167], v[208:211], v[6:9]
	v_mfma_f32_16x16x32_bf16 v[2:5], v[172:175], v[208:211], v[2:5]
	v_mfma_f32_16x16x32_bf16 v[54:57], v[168:171], v[188:191], v[54:57]
	v_mfma_f32_16x16x32_bf16 v[50:53], v[180:183], v[188:191], v[50:53]
	v_mfma_f32_16x16x32_bf16 v[38:41], v[168:171], v[196:199], v[38:41]
	v_mfma_f32_16x16x32_bf16 v[34:37], v[180:183], v[196:199], v[34:37]
	v_mfma_f32_16x16x32_bf16 v[22:25], v[168:171], v[204:207], v[22:25]
	v_mfma_f32_16x16x32_bf16 v[18:21], v[180:183], v[204:207], v[18:21]
	v_mfma_f32_16x16x32_bf16 v[6:9], v[168:171], v[212:215], v[6:9]
	s_setprio 0
	v_mfma_f32_16x16x32_bf16 v[2:5], v[180:183], v[212:215], v[2:5]
	s_barrier
	s_add_i32 s9, 0, 0x18000
	s_add_i32 s78, 0, 0x1c000
	v_add_u32_e32 v160, s9, v177
	v_add_u32_e32 v180, s78, v177
	ds_read_b128 v[140:143], v160
	ds_read_b128 v[144:147], v160 offset:1024
	ds_read_b128 v[156:159], v160 offset:2048
	ds_read_b128 v[160:163], v160 offset:3072
	ds_read_b128 v[164:167], v180
	ds_read_b128 v[168:171], v180 offset:1024
	ds_read_b128 v[172:175], v180 offset:2048
	ds_read_b128 v[180:183], v180 offset:3072
	s_add_u32 s24, s38, 0xb0000
	s_addc_u32 s25, s39, 0
	s_mov_b32 m0, s50
	v_lshl_add_u64 v[220:221], s[24:25], 0, v[130:131]
	ds_read_b128 v[184:187], v179 offset:32768
	ds_read_b128 v[188:191], v179 offset:33792
	ds_read_b128 v[192:195], v179 offset:34816
	ds_read_b128 v[196:199], v179 offset:35840
	ds_read_b128 v[200:203], v179 offset:36864
	ds_read_b128 v[204:207], v179 offset:37888
	ds_read_b128 v[208:211], v179 offset:38912
	ds_read_b128 v[212:215], v179 offset:39936
	global_load_lds_dwordx4 v[220:221], off
	s_mov_b32 m0, s51
	v_lshl_add_u64 v[220:221], s[24:25], 0, v[132:133]
	global_load_lds_dwordx4 v[220:221], off
	s_waitcnt vmcnt(8)
	s_waitcnt lgkmcnt(0)
	s_setprio 1
	s_barrier
	v_mfma_f32_16x16x32_bf16 v[126:129], v[140:143], v[184:187], v[126:129]
	v_mfma_f32_16x16x32_bf16 v[122:125], v[156:159], v[184:187], v[122:125]
	v_mfma_f32_16x16x32_bf16 v[110:113], v[140:143], v[192:195], v[110:113]
	v_mfma_f32_16x16x32_bf16 v[106:109], v[156:159], v[192:195], v[106:109]
	v_mfma_f32_16x16x32_bf16 v[94:97], v[140:143], v[200:203], v[94:97]
	v_mfma_f32_16x16x32_bf16 v[90:93], v[156:159], v[200:203], v[90:93]
	v_mfma_f32_16x16x32_bf16 v[78:81], v[140:143], v[208:211], v[78:81]
	v_mfma_f32_16x16x32_bf16 v[74:77], v[156:159], v[208:211], v[74:77]
	v_mfma_f32_16x16x32_bf16 v[126:129], v[144:147], v[188:191], v[126:129]
	v_mfma_f32_16x16x32_bf16 v[122:125], v[160:163], v[188:191], v[122:125]
	v_mfma_f32_16x16x32_bf16 v[110:113], v[144:147], v[196:199], v[110:113]
	v_mfma_f32_16x16x32_bf16 v[106:109], v[160:163], v[196:199], v[106:109]
	v_mfma_f32_16x16x32_bf16 v[94:97], v[144:147], v[204:207], v[94:97]
	v_mfma_f32_16x16x32_bf16 v[90:93], v[160:163], v[204:207], v[90:93]
	v_mfma_f32_16x16x32_bf16 v[78:81], v[144:147], v[212:215], v[78:81]
	v_mfma_f32_16x16x32_bf16 v[74:77], v[160:163], v[212:215], v[74:77]
	v_mfma_f32_16x16x32_bf16 v[118:121], v[164:167], v[184:187], v[118:121]
	v_mfma_f32_16x16x32_bf16 v[114:117], v[172:175], v[184:187], v[114:117]
	v_mfma_f32_16x16x32_bf16 v[102:105], v[164:167], v[192:195], v[102:105]
	v_mfma_f32_16x16x32_bf16 v[98:101], v[172:175], v[192:195], v[98:101]
	v_mfma_f32_16x16x32_bf16 v[86:89], v[164:167], v[200:203], v[86:89]
	v_mfma_f32_16x16x32_bf16 v[82:85], v[172:175], v[200:203], v[82:85]
	v_mfma_f32_16x16x32_bf16 v[70:73], v[164:167], v[208:211], v[70:73]
	v_mfma_f32_16x16x32_bf16 v[66:69], v[172:175], v[208:211], v[66:69]
	v_mfma_f32_16x16x32_bf16 v[118:121], v[168:171], v[188:191], v[118:121]
	v_mfma_f32_16x16x32_bf16 v[114:117], v[180:183], v[188:191], v[114:117]
	v_mfma_f32_16x16x32_bf16 v[102:105], v[168:171], v[196:199], v[102:105]
	v_mfma_f32_16x16x32_bf16 v[98:101], v[180:183], v[196:199], v[98:101]
	v_mfma_f32_16x16x32_bf16 v[86:89], v[168:171], v[204:207], v[86:89]
	v_mfma_f32_16x16x32_bf16 v[82:85], v[180:183], v[204:207], v[82:85]
	v_mfma_f32_16x16x32_bf16 v[70:73], v[168:171], v[212:215], v[70:73]
	s_setprio 0
	v_mfma_f32_16x16x32_bf16 v[66:69], v[180:183], v[212:215], v[66:69]
	s_barrier
	s_add_i32 s9, s9, s28
	v_lshl_add_u64 v[148:149], v[148:149], 0, s[70:71]
	s_mov_b32 m0, s9
	ds_read_b128 v[184:187], v179 offset:49152
	ds_read_b128 v[188:191], v179 offset:50176
	ds_read_b128 v[192:195], v179 offset:51200
	ds_read_b128 v[196:199], v179 offset:52224
	ds_read_b128 v[200:203], v179 offset:53248
	ds_read_b128 v[204:207], v179 offset:54272
	ds_read_b128 v[208:211], v179 offset:55296
	ds_read_b128 v[212:215], v179 offset:56320
	global_load_lds_dwordx4 v[148:149], off
	s_add_i32 m0, s9, 0x2000
	s_add_u32 s24, s26, 0xb0080
	v_lshl_add_u64 v[148:149], v[150:151], 0, s[70:71]
	s_addc_u32 s25, s27, 0
	s_add_i32 s9, s78, s28
	global_load_lds_dwordx4 v[148:149], off
	s_mov_b32 m0, s9
	v_lshl_add_u64 v[148:149], s[24:25], 0, v[0:1]
	global_load_lds_dwordx4 v[148:149], off
	s_add_i32 m0, s9, 0x2000
	v_lshl_add_u64 v[148:149], s[24:25], 0, v[134:135]
	global_load_lds_dwordx4 v[148:149], off
	s_mov_b32 m0, s52
	v_lshl_add_u64 v[148:149], v[216:217], 0, s[70:71]
	global_load_lds_dwordx4 v[148:149], off
	s_mov_b32 m0, s53
	v_lshl_add_u64 v[148:149], v[218:219], 0, s[70:71]
	global_load_lds_dwordx4 v[148:149], off
	s_waitcnt vmcnt(8)
	s_waitcnt lgkmcnt(0)
	s_setprio 1
	s_barrier
	v_mfma_f32_16x16x32_bf16 v[62:65], v[140:143], v[184:187], v[62:65]
	v_mfma_f32_16x16x32_bf16 v[58:61], v[156:159], v[184:187], v[58:61]
	v_mfma_f32_16x16x32_bf16 v[46:49], v[140:143], v[192:195], v[46:49]
	v_mfma_f32_16x16x32_bf16 v[42:45], v[156:159], v[192:195], v[42:45]
	v_mfma_f32_16x16x32_bf16 v[30:33], v[140:143], v[200:203], v[30:33]
	v_mfma_f32_16x16x32_bf16 v[26:29], v[156:159], v[200:203], v[26:29]
	v_mfma_f32_16x16x32_bf16 v[14:17], v[140:143], v[208:211], v[14:17]
	v_mfma_f32_16x16x32_bf16 v[10:13], v[156:159], v[208:211], v[10:13]
	v_mfma_f32_16x16x32_bf16 v[62:65], v[144:147], v[188:191], v[62:65]
	v_mfma_f32_16x16x32_bf16 v[58:61], v[160:163], v[188:191], v[58:61]
	v_mfma_f32_16x16x32_bf16 v[46:49], v[144:147], v[196:199], v[46:49]
	v_mfma_f32_16x16x32_bf16 v[42:45], v[160:163], v[196:199], v[42:45]
	v_mfma_f32_16x16x32_bf16 v[30:33], v[144:147], v[204:207], v[30:33]
	v_mfma_f32_16x16x32_bf16 v[26:29], v[160:163], v[204:207], v[26:29]
	v_mfma_f32_16x16x32_bf16 v[14:17], v[144:147], v[212:215], v[14:17]
	v_mfma_f32_16x16x32_bf16 v[10:13], v[160:163], v[212:215], v[10:13]
	v_mfma_f32_16x16x32_bf16 v[54:57], v[164:167], v[184:187], v[54:57]
	v_mfma_f32_16x16x32_bf16 v[50:53], v[172:175], v[184:187], v[50:53]
	v_mfma_f32_16x16x32_bf16 v[38:41], v[164:167], v[192:195], v[38:41]
	v_mfma_f32_16x16x32_bf16 v[34:37], v[172:175], v[192:195], v[34:37]
	v_mfma_f32_16x16x32_bf16 v[22:25], v[164:167], v[200:203], v[22:25]
	v_mfma_f32_16x16x32_bf16 v[18:21], v[172:175], v[200:203], v[18:21]
	v_mfma_f32_16x16x32_bf16 v[6:9], v[164:167], v[208:211], v[6:9]
	v_mfma_f32_16x16x32_bf16 v[2:5], v[172:175], v[208:211], v[2:5]
	v_mfma_f32_16x16x32_bf16 v[54:57], v[168:171], v[188:191], v[54:57]
	v_mfma_f32_16x16x32_bf16 v[50:53], v[180:183], v[188:191], v[50:53]
	v_mfma_f32_16x16x32_bf16 v[38:41], v[168:171], v[196:199], v[38:41]
	v_mfma_f32_16x16x32_bf16 v[34:37], v[180:183], v[196:199], v[34:37]
	v_mfma_f32_16x16x32_bf16 v[22:25], v[168:171], v[204:207], v[22:25]
	v_mfma_f32_16x16x32_bf16 v[18:21], v[180:183], v[204:207], v[18:21]
	v_mfma_f32_16x16x32_bf16 v[6:9], v[168:171], v[212:215], v[6:9]
	s_setprio 0
	v_mfma_f32_16x16x32_bf16 v[2:5], v[180:183], v[212:215], v[2:5]
	s_barrier
	s_add_u32 s94, s94, 0x100
	s_addc_u32 s95, s95, 0
	s_cmp_ge_u32 s96, s92
	s_mov_b64 s[24:25], s[36:37]
	s_mov_b32 s26, s96
	s_cbranch_scc0 .LBB0_1054
	s_and_b64 vcc, exec, s[12:13]
	s_cbranch_vccz .LBB0_1057
